# RWKV scan: k/e interleaved in LDS (two conflict-free arrays), dot products as packed f32 pairs
# speedup vs baseline: 1.0180x; 1.0180x over previous
.LBB0_185:
	s_and_b32 s17, s16, 1
	s_and_saveexec_b64 s[0:1], s[36:37]
	s_xor_b64 s[8:9], exec, s[0:1]
	s_cbranch_execz .LBB0_203
	s_ashr_i32 s2, s16, 5
	v_readlane_b32 s0, v251, 28
	s_ashr_i32 s3, s2, 31
	s_bfe_u32 s12, s16, 0x40001
	v_readlane_b32 s1, v251, 29
	s_lshl_b64 s[10:11], s[2:3], 11
	s_mov_b32 s15, s1
	s_lshl_b32 s14, s12, 7
	s_lshl_b32 s18, s12, 6
	v_lshl_add_u64 v[16:17], s[10:11], 0, v[104:105]
	v_lshl_add_u64 v[34:35], v[106:107], 0, s[14:15]
	s_movk_i32 s13, 0x1800
	v_lshl_add_u64 v[36:37], v[108:109], 0, s[14:15]
	v_or_b32_e32 v2, s18, v1
	v_readlane_b32 s40, v251, 9
	v_mad_u64_u32 v[14:15], s[0:1], v16, s13, v[34:35]
	v_mad_u64_u32 v[18:19], s[0:1], v16, s13, v[36:37]
	v_lshlrev_b32_e32 v12, 2, v2
	v_readlane_b32 s44, v251, 13
	v_readlane_b32 s45, v251, 14
	v_mad_i32_i24 v15, v17, s13, v15
	v_mad_i32_i24 v19, v17, s13, v19
	v_readlane_b32 s42, v251, 11
	v_readlane_b32 s43, v251, 12
	v_add_co_u32_e32 v10, vcc, s73, v14
	global_load_dwordx4 v[2:5], v12, s[44:45]
	global_load_dwordx2 v[20:21], v[14:15], off
	global_load_dwordx2 v[22:23], v[14:15], off offset:2048
	global_load_dwordx2 v[30:31], v[18:19], off
	global_load_dwordx4 v[6:9], v12, s[42:43]
	global_load_dwordx2 v[32:33], v[18:19], off offset:2048
	v_addc_co_u32_e32 v11, vcc, 0, v15, vcc
	v_readlane_b32 s46, v251, 15
	v_readlane_b32 s47, v251, 16
	global_load_dwordx2 v[24:25], v[10:11], off
	s_nop 3
	global_load_dwordx4 v[10:13], v12, s[46:47]
	s_waitcnt vmcnt(9)
	v_or_b32_e32 v26, s17, v1
	v_cmp_eq_u32_e64 s[0:1], 0, v26
	s_lshl_b32 s19, s12, 2
	v_readlane_b32 s12, v248, 15
	v_readlane_b32 s13, v248, 16
	s_add_u32 s12, s12, s19
	s_addc_u32 s13, s13, 0
	v_lshlrev_b64 v[16:17], 6, v[16:17]
	s_mov_b64 s[24:25], s[14:15]
	v_readlane_b32 s41, v251, 10
	v_readlane_b32 s48, v251, 17
	v_readlane_b32 s49, v251, 18
	v_readlane_b32 s50, v251, 19
	v_readlane_b32 s51, v251, 20
	v_readlane_b32 s52, v251, 21
	v_readlane_b32 s53, v251, 22
	v_readlane_b32 s54, v251, 23
	v_readlane_b32 s55, v251, 24
	s_waitcnt vmcnt(7)
	v_pk_add_f32 v[38:39], v[2:3], 1.0 op_sel_hi:[1,0] neg_lo:[1,0] neg_hi:[1,0]
	s_waitcnt vmcnt(5)
	v_lshlrev_b32_e32 v28, 16, v22
	v_and_b32_e32 v29, 0xffff0000, v22
	s_waitcnt vmcnt(2)
	v_lshlrev_b32_e32 v50, 16, v32
	v_and_b32_e32 v51, 0xffff0000, v32
	v_lshlrev_b32_e32 v26, 16, v20
	v_and_b32_e32 v27, 0xffff0000, v20
	v_lshlrev_b32_e32 v54, 16, v21
	v_and_b32_e32 v55, 0xffff0000, v21
	v_lshlrev_b32_e32 v43, 16, v30
	v_and_b32_e32 v45, 0xffff0000, v30
	v_pk_mul_f32 v[20:21], v[6:7], v[28:29]
	s_waitcnt vmcnt(1)
	v_and_b32_e32 v32, 0xffff0000, v25
	v_lshlrev_b32_e32 v30, 16, v25
	v_and_b32_e32 v44, 0xffff0000, v24
	v_lshlrev_b32_e32 v42, 16, v24
	v_pk_fma_f32 v[24:25], v[50:51], v[2:3], v[38:39]
	v_pk_add_f32 v[40:41], v[4:5], 1.0 op_sel_hi:[1,0] neg_lo:[1,0] neg_hi:[1,0]
	v_lshlrev_b32_e32 v56, 16, v33
	v_and_b32_e32 v57, 0xffff0000, v33
	v_pk_mul_f32 v[60:61], v[20:21], v[50:51]
	v_pk_mul_f32 v[50:51], v[24:25], v[28:29]
	v_lshlrev_b32_e32 v52, 16, v23
	v_and_b32_e32 v53, 0xffff0000, v23
	v_lshlrev_b32_e32 v48, 16, v31
	v_and_b32_e32 v31, 0xffff0000, v31
	v_pk_fma_f32 v[58:59], v[56:57], v[4:5], v[40:41]
	v_pk_mul_f32 v[24:25], v[50:51], v[26:27]
	v_pk_mul_f32 v[22:23], v[8:9], v[52:53]
	v_fma_f32 v33, v20, v20, 0
	v_exp_f32_e32 v49, v31
	v_pk_mul_f32 v[52:53], v[58:59], v[52:53]
	v_fma_f32 v31, v60, v26, 0
	v_fma_f32 v64, v50, v26, 0
	s_waitcnt vmcnt(0)
	v_fma_f32 v24, v24, v10, 0
	v_pk_mul_f32 v[56:57], v[22:23], v[56:57]
	v_fmac_f32_e32 v33, v21, v21
	v_pk_mul_f32 v[28:29], v[52:53], v[54:55]
	v_fmac_f32_e32 v31, v61, v27
	v_fmac_f32_e32 v64, v51, v27
	v_fmac_f32_e32 v24, v25, v11
	v_exp_f32_e32 v48, v48
	v_fmac_f32_e32 v33, v22, v22
	v_fmac_f32_e32 v31, v56, v54
	v_fmac_f32_e32 v64, v52, v54
	v_fmac_f32_e32 v24, v28, v12
	v_fmac_f32_e32 v33, v23, v23
	v_fmac_f32_e32 v31, v57, v55
	v_fmac_f32_e32 v64, v53, v55
	v_fmac_f32_e32 v24, v29, v13
	s_nop 1
	v_add_f32_dpp v33, v33, v33 quad_perm:[1,0,3,2] row_mask:0xf bank_mask:0xf
	v_add_f32_dpp v24, v24, v24 quad_perm:[1,0,3,2] row_mask:0xf bank_mask:0xf
	v_add_f32_dpp v31, v31, v31 quad_perm:[1,0,3,2] row_mask:0xf bank_mask:0xf
	v_add_f32_dpp v64, v64, v64 quad_perm:[1,0,3,2] row_mask:0xf bank_mask:0xf
	v_add_f32_dpp v33, v33, v33 quad_perm:[2,3,0,1] row_mask:0xf bank_mask:0xf
	v_add_f32_dpp v24, v24, v24 quad_perm:[2,3,0,1] row_mask:0xf bank_mask:0xf
	v_add_f32_dpp v31, v31, v31 quad_perm:[2,3,0,1] row_mask:0xf bank_mask:0xf
	v_add_f32_dpp v64, v64, v64 quad_perm:[2,3,0,1] row_mask:0xf bank_mask:0xf
	v_add_f32_dpp v33, v33, v33 row_half_mirror row_mask:0xf bank_mask:0xf
	v_add_f32_dpp v24, v24, v24 row_half_mirror row_mask:0xf bank_mask:0xf
	v_add_f32_dpp v31, v31, v31 row_half_mirror row_mask:0xf bank_mask:0xf
	v_add_f32_dpp v64, v64, v64 row_half_mirror row_mask:0xf bank_mask:0xf
	v_add_f32_dpp v33, v33, v33 row_mirror row_mask:0xf bank_mask:0xf
	v_add_f32_dpp v24, v24, v24 row_mirror row_mask:0xf bank_mask:0xf
	v_add_f32_dpp v31, v31, v31 row_mirror row_mask:0xf bank_mask:0xf
	v_add_f32_dpp v64, v64, v64 row_mirror row_mask:0xf bank_mask:0xf
	s_nop 0
	v_exp_f32_e32 v46, v43
	v_max_f32_e32 v25, v33, v33
	v_max_f32_e32 v25, 0x179abe15, v25
	v_exp_f32_e32 v47, v45
	v_pk_mul_f32 v[62:63], v[48:49], v[54:55]
	v_rsq_f32_e32 v54, v25
	ds_write_b128 v126, v[50:53] offset:16384
	ds_write_b128 v126, v[46:49] offset:24576
	v_pk_mul_f32 v[58:59], v[46:47], v[26:27]
	v_mul_f32_e32 v43, v64, v42
	v_pk_mul_f32 v[20:21], v[20:21], v[54:55] op_sel_hi:[1,0]
	v_pk_mul_f32 v[22:23], v[22:23], v[54:55] op_sel_hi:[1,0]
	v_mul_f32_e64 v46, v31, -v54
	v_pk_mul_f32 v[28:29], v[56:57], v[54:55] op_sel_hi:[1,0]
	v_pk_mul_f32 v[26:27], v[60:61], v[54:55] op_sel_hi:[1,0]
	v_pk_fma_f32 v[48:49], v[46:47], v[22:23], v[62:63] op_sel_hi:[0,1,1]
	v_pk_fma_f32 v[46:47], v[46:47], v[20:21], v[58:59] op_sel_hi:[0,1,1]
	ds_write_b128 v126, v[26:29] offset:32768
	v_add_u32_e32 v201, 0x2000, v126
	ds_write2_b32 v126, v20, v46 offset1:1
	ds_write2_b32 v126, v21, v47 offset0:2 offset1:3
	ds_write2_b32 v201, v22, v48 offset1:1
	ds_write2_b32 v201, v23, v49 offset0:2 offset1:3
	v_mul_f32_e32 v45, v64, v44
	v_add_u32_e32 v20, v124, v127
	v_mul_f32_e32 v31, v64, v30
	v_mul_f32_e32 v33, v64, v32
	v_lshl_add_u64 v[22:23], s[12:13], 0, v[16:17]
	ds_write_b128 v20, v[42:45] offset:40960
	ds_write_b128 v20, v[30:33] offset:40976
	s_and_saveexec_b64 s[14:15], s[0:1]
	s_cbranch_execz .LBB0_188
	global_store_dword v[22:23], v24, off
.LBB0_188:
	s_or_b64 exec, exec, s[14:15]
	v_add_co_u32_e32 v24, vcc, 0x18000, v14
	s_mov_b64 s[14:15], 0x18000
	s_nop 0
	v_addc_co_u32_e32 v25, vcc, 0, v15, vcc
	v_lshl_add_u64 v[16:17], v[14:15], 0, s[14:15]
	v_add_co_u32_e32 v14, vcc, 0x19000, v14
	global_load_dwordx2 v[24:25], v[24:25], off
	s_nop 0
	global_load_dwordx2 v[32:33], v[16:17], off offset:2048
	v_addc_co_u32_e32 v15, vcc, 0, v15, vcc
	global_load_dwordx2 v[54:55], v[14:15], off
	v_add_co_u32_e32 v14, vcc, 0x18000, v18
	v_lshl_add_u64 v[20:21], v[18:19], 0, s[14:15]
	s_nop 0
	v_addc_co_u32_e32 v15, vcc, 0, v19, vcc
	global_load_dwordx2 v[14:15], v[14:15], off
	s_nop 0
	global_load_dwordx2 v[18:19], v[20:21], off offset:2048
	s_waitcnt vmcnt(4)
	v_lshlrev_b32_e32 v50, 16, v25
	s_waitcnt vmcnt(3)
	v_and_b32_e32 v17, 0xffff0000, v32
	v_and_b32_e32 v51, 0xffff0000, v25
	s_waitcnt vmcnt(1)
	v_lshlrev_b32_e32 v16, 16, v14
	s_waitcnt vmcnt(0)
	v_lshlrev_b32_e32 v42, 16, v18
	v_and_b32_e32 v43, 0xffff0000, v18
	v_and_b32_e32 v14, 0xffff0000, v14
	v_exp_f32_e32 v26, v16
	v_lshlrev_b32_e32 v16, 16, v32
	v_pk_fma_f32 v[28:29], v[42:43], v[2:3], v[38:39]
	v_lshlrev_b32_e32 v44, 16, v15
	v_and_b32_e32 v45, 0xffff0000, v15
	v_exp_f32_e32 v27, v14
	v_lshlrev_b32_e32 v14, 16, v24
	v_and_b32_e32 v15, 0xffff0000, v24
	v_pk_mul_f32 v[30:31], v[28:29], v[16:17]
	v_lshlrev_b32_e32 v18, 16, v19
	v_pk_mul_f32 v[28:29], v[30:31], v[14:15]
	v_and_b32_e32 v19, 0xffff0000, v19
	v_fma_f32 v24, v28, v10, 0
	v_lshlrev_b32_e32 v32, 16, v33
	v_and_b32_e32 v33, 0xffff0000, v33
	v_pk_fma_f32 v[46:47], v[18:19], v[4:5], v[40:41]
	v_fmac_f32_e32 v24, v29, v11
	v_exp_f32_e32 v28, v44
	v_exp_f32_e32 v29, v45
	v_pk_mul_f32 v[44:45], v[8:9], v[32:33]
	v_pk_mul_f32 v[32:33], v[46:47], v[32:33]
	v_pk_mul_f32 v[20:21], v[6:7], v[16:17]
	v_pk_mul_f32 v[46:47], v[32:33], v[50:51]
	v_fma_f32 v48, v20, v20, 0
	v_fmac_f32_e32 v24, v46, v12
	v_fmac_f32_e32 v24, v47, v13
	v_pk_mul_f32 v[46:47], v[20:21], v[42:43]
	v_fma_f32 v17, v30, v14, 0
	v_fma_f32 v25, v46, v14, 0
	v_fmac_f32_e32 v48, v21, v21
	v_fmac_f32_e32 v17, v31, v15
	v_fmac_f32_e32 v25, v47, v15
	v_pk_mul_f32 v[18:19], v[44:45], v[18:19]
	v_fmac_f32_e32 v48, v44, v44
	v_fmac_f32_e32 v17, v32, v50
	v_fmac_f32_e32 v25, v18, v50
	v_fmac_f32_e32 v48, v45, v45
	v_fmac_f32_e32 v17, v33, v51
	v_fmac_f32_e32 v25, v19, v51
	s_nop 1
	v_add_f32_dpp v48, v48, v48 quad_perm:[1,0,3,2] row_mask:0xf bank_mask:0xf
	v_add_f32_dpp v24, v24, v24 quad_perm:[1,0,3,2] row_mask:0xf bank_mask:0xf
	v_add_f32_dpp v25, v25, v25 quad_perm:[1,0,3,2] row_mask:0xf bank_mask:0xf
	v_add_f32_dpp v17, v17, v17 quad_perm:[1,0,3,2] row_mask:0xf bank_mask:0xf
	v_add_f32_dpp v48, v48, v48 quad_perm:[2,3,0,1] row_mask:0xf bank_mask:0xf
	v_add_f32_dpp v24, v24, v24 quad_perm:[2,3,0,1] row_mask:0xf bank_mask:0xf
	v_add_f32_dpp v25, v25, v25 quad_perm:[2,3,0,1] row_mask:0xf bank_mask:0xf
	v_add_f32_dpp v17, v17, v17 quad_perm:[2,3,0,1] row_mask:0xf bank_mask:0xf
	v_add_f32_dpp v48, v48, v48 row_half_mirror row_mask:0xf bank_mask:0xf
	v_add_f32_dpp v24, v24, v24 row_half_mirror row_mask:0xf bank_mask:0xf
	v_add_f32_dpp v25, v25, v25 row_half_mirror row_mask:0xf bank_mask:0xf
	v_add_f32_dpp v17, v17, v17 row_half_mirror row_mask:0xf bank_mask:0xf
	v_add_f32_dpp v48, v48, v48 row_mirror row_mask:0xf bank_mask:0xf
	v_add_f32_dpp v24, v24, v24 row_mirror row_mask:0xf bank_mask:0xf
	v_add_f32_dpp v25, v25, v25 row_mirror row_mask:0xf bank_mask:0xf
	v_add_f32_dpp v17, v17, v17 row_mirror row_mask:0xf bank_mask:0xf
	s_nop 0
	v_pk_mul_f32 v[14:15], v[26:27], v[14:15]
	v_max_f32_e32 v16, v48, v48
	v_max_f32_e32 v16, 0x179abe15, v16
	v_rsq_f32_e32 v16, v16
	s_nop 0
	v_pk_mul_f32 v[42:43], v[20:21], v[16:17] op_sel_hi:[1,0]
	v_pk_mul_f32 v[44:45], v[44:45], v[16:17] op_sel_hi:[1,0]
	v_pk_mul_f32 v[48:49], v[18:19], v[16:17] op_sel_hi:[1,0]
	v_pk_mul_f32 v[46:47], v[46:47], v[16:17] op_sel_hi:[1,0]
	v_pk_mul_f32 v[18:19], v[28:29], v[50:51]
	v_mul_f32_e64 v16, v25, -v16
	v_pk_fma_f32 v[52:53], v[16:17], v[44:45], v[18:19] op_sel_hi:[0,1,1]
	v_pk_fma_f32 v[50:51], v[16:17], v[42:43], v[14:15] op_sel_hi:[0,1,1]
	v_and_b32_e32 v16, 0xffff0000, v55
	v_lshlrev_b32_e32 v14, 16, v55
	v_and_b32_e32 v20, 0xffff0000, v54
	v_lshlrev_b32_e32 v18, 16, v54
	v_mul_f32_e32 v19, v17, v18
	v_mul_f32_e32 v21, v17, v20
	v_add_u32_e32 v25, v124, v130
	v_mul_f32_e32 v15, v17, v14
	v_mul_f32_e32 v17, v17, v16
	ds_write_b128 v129, v[46:49] offset:32768
	ds_write_b128 v129, v[30:33] offset:16384
	ds_write_b128 v129, v[26:29] offset:24576
	v_add_u32_e32 v201, 0x2000, v129
	ds_write2_b32 v129, v42, v50 offset1:1
	ds_write2_b32 v129, v43, v51 offset0:2 offset1:3
	ds_write2_b32 v201, v44, v52 offset1:1
	ds_write2_b32 v201, v45, v53 offset0:2 offset1:3
	ds_write_b128 v25, v[18:21] offset:40960
	ds_write_b128 v25, v[14:17] offset:40976
	s_and_saveexec_b64 s[14:15], s[0:1]
	s_cbranch_execz .LBB0_190
	global_store_dword v[22:23], v24, off offset:1024
.LBB0_190:
	s_or_b64 exec, exec, s[14:15]
	v_lshl_add_u64 v[42:43], v[104:105], 0, s[10:11]
	v_lshl_add_u64 v[46:47], v[42:43], 0, 32
	s_movk_i32 s20, 0x1800
	v_mad_u64_u32 v[14:15], s[14:15], v46, s20, v[34:35]
	v_mad_i32_i24 v15, v47, s20, v15
	v_add_co_u32_e32 v18, vcc, s73, v14
	v_mad_u64_u32 v[16:17], s[14:15], v46, s20, v[36:37]
	s_nop 0
	v_addc_co_u32_e32 v19, vcc, 0, v15, vcc
	v_mad_i32_i24 v17, v47, s20, v17
	global_load_dwordx2 v[20:21], v[14:15], off
	global_load_dwordx2 v[22:23], v[14:15], off offset:2048
	global_load_dwordx2 v[54:55], v[18:19], off
	s_nop 0
	global_load_dwordx2 v[18:19], v[16:17], off
	global_load_dwordx2 v[24:25], v[16:17], off offset:2048
	s_mov_b64 s[14:15], 0x18000
	v_lshl_add_u64 v[26:27], v[14:15], 0, s[14:15]
	v_lshl_add_u64 v[28:29], v[16:17], 0, s[14:15]
	s_mov_b32 s14, 0x19000
	v_add_co_u32_e32 v14, vcc, s14, v14
	s_mov_b32 s14, 0x18000
	s_nop 0
	v_addc_co_u32_e32 v15, vcc, 0, v15, vcc
	global_load_dwordx2 v[50:51], v[14:15], off offset:-4096
	global_load_dwordx2 v[48:49], v[26:27], off offset:2048
	global_load_dwordx2 v[44:45], v[14:15], off
	v_add_co_u32_e32 v14, vcc, s14, v16
	s_waitcnt vmcnt(7)
	v_lshlrev_b32_e32 v60, 16, v20
	v_addc_co_u32_e32 v15, vcc, 0, v17, vcc
	global_load_dwordx2 v[56:57], v[14:15], off
	global_load_dwordx2 v[52:53], v[28:29], off offset:2048
	s_waitcnt vmcnt(5)
	v_lshlrev_b32_e32 v28, 16, v24
	v_and_b32_e32 v29, 0xffff0000, v24
	v_lshlrev_b32_e32 v14, 16, v18
	v_and_b32_e32 v15, 0xffff0000, v18
	v_lshlrev_b32_e32 v30, 16, v19
	v_and_b32_e32 v31, 0xffff0000, v19
	v_lshlrev_b32_e32 v16, 16, v22
	v_and_b32_e32 v17, 0xffff0000, v22
	v_pk_fma_f32 v[18:19], v[28:29], v[2:3], v[38:39]
	v_and_b32_e32 v61, 0xffff0000, v20
	v_pk_mul_f32 v[18:19], v[18:19], v[16:17]
	v_pk_mul_f32 v[26:27], v[6:7], v[16:17]
	v_pk_mul_f32 v[16:17], v[18:19], v[60:61]
	v_lshlrev_b32_e32 v24, 16, v25
	v_fma_f32 v58, v16, v10, 0
	v_and_b32_e32 v25, 0xffff0000, v25
	v_fmac_f32_e32 v58, v17, v11
	v_exp_f32_e32 v16, v30
	v_exp_f32_e32 v17, v31
	v_lshlrev_b32_e32 v62, 16, v21
	v_and_b32_e32 v63, 0xffff0000, v21
	v_lshlrev_b32_e32 v20, 16, v23
	v_and_b32_e32 v21, 0xffff0000, v23
	v_pk_fma_f32 v[30:31], v[24:25], v[4:5], v[40:41]
	v_pk_mul_f32 v[64:65], v[26:27], v[28:29]
	v_fma_f32 v32, v26, v26, 0
	v_fma_f32 v59, v18, v60, 0
	v_pk_mul_f32 v[22:23], v[8:9], v[20:21]
	v_pk_mul_f32 v[20:21], v[30:31], v[20:21]
	v_fma_f32 v67, v64, v60, 0
	v_fmac_f32_e32 v32, v27, v27
	v_fmac_f32_e32 v59, v19, v61
	v_pk_mul_f32 v[30:31], v[20:21], v[62:63]
	v_fmac_f32_e32 v67, v65, v61
	v_pk_mul_f32 v[24:25], v[22:23], v[24:25]
	v_fmac_f32_e32 v32, v22, v22
	v_fmac_f32_e32 v58, v30, v12
	v_fmac_f32_e32 v59, v20, v62
	v_fmac_f32_e32 v67, v24, v62
	v_fmac_f32_e32 v32, v23, v23
	v_fmac_f32_e32 v58, v31, v13
	v_fmac_f32_e32 v59, v21, v63
	v_fmac_f32_e32 v67, v25, v63
	s_waitcnt lgkmcnt(0)
	s_barrier
	s_nop 1
	v_add_f32_dpp v32, v32, v32 quad_perm:[1,0,3,2] row_mask:0xf bank_mask:0xf
	v_add_f32_dpp v58, v58, v58 quad_perm:[1,0,3,2] row_mask:0xf bank_mask:0xf
	v_add_f32_dpp v67, v67, v67 quad_perm:[1,0,3,2] row_mask:0xf bank_mask:0xf
	v_add_f32_dpp v59, v59, v59 quad_perm:[1,0,3,2] row_mask:0xf bank_mask:0xf
	v_add_f32_dpp v32, v32, v32 quad_perm:[2,3,0,1] row_mask:0xf bank_mask:0xf
	v_add_f32_dpp v58, v58, v58 quad_perm:[2,3,0,1] row_mask:0xf bank_mask:0xf
	v_add_f32_dpp v67, v67, v67 quad_perm:[2,3,0,1] row_mask:0xf bank_mask:0xf
	v_add_f32_dpp v59, v59, v59 quad_perm:[2,3,0,1] row_mask:0xf bank_mask:0xf
	v_add_f32_dpp v32, v32, v32 row_half_mirror row_mask:0xf bank_mask:0xf
	v_add_f32_dpp v58, v58, v58 row_half_mirror row_mask:0xf bank_mask:0xf
	v_add_f32_dpp v67, v67, v67 row_half_mirror row_mask:0xf bank_mask:0xf
	v_add_f32_dpp v59, v59, v59 row_half_mirror row_mask:0xf bank_mask:0xf
	v_add_f32_dpp v32, v32, v32 row_mirror row_mask:0xf bank_mask:0xf
	v_add_f32_dpp v58, v58, v58 row_mirror row_mask:0xf bank_mask:0xf
	v_add_f32_dpp v67, v67, v67 row_mirror row_mask:0xf bank_mask:0xf
	v_add_f32_dpp v59, v59, v59 row_mirror row_mask:0xf bank_mask:0xf
	s_nop 0
	v_exp_f32_e32 v14, v14
	v_max_f32_e32 v28, v32, v32
	v_max_f32_e32 v28, 0x179abe15, v28
	v_exp_f32_e32 v15, v15
	v_rsq_f32_e32 v66, v28
	s_nop 0
	v_pk_mul_f32 v[30:31], v[26:27], v[66:67] op_sel_hi:[1,0]
	v_pk_mul_f32 v[32:33], v[22:23], v[66:67] op_sel_hi:[1,0]
	v_pk_mul_f32 v[28:29], v[24:25], v[66:67] op_sel_hi:[1,0]
	v_pk_mul_f32 v[22:23], v[14:15], v[60:61]
	v_pk_mul_f32 v[24:25], v[16:17], v[62:63]
	v_mul_f32_e64 v60, v67, -v66
	v_pk_mul_f32 v[26:27], v[64:65], v[66:67] op_sel_hi:[1,0]
	v_pk_fma_f32 v[24:25], v[60:61], v[32:33], v[24:25] op_sel_hi:[0,1,1]
	v_pk_fma_f32 v[22:23], v[60:61], v[30:31], v[22:23] op_sel_hi:[0,1,1]
	v_and_b32_e32 v62, 0xffff0000, v55
	v_lshlrev_b32_e32 v60, 16, v55
	v_and_b32_e32 v66, 0xffff0000, v54
	v_lshlrev_b32_e32 v64, 16, v54
	ds_write_b128 v133, v[26:29] offset:32768
	ds_write_b128 v133, v[18:21] offset:16384
	ds_write_b128 v133, v[14:17] offset:24576
	v_add_u32_e32 v201, 0x2000, v133
	ds_write2_b32 v133, v30, v22 offset1:1
	ds_write2_b32 v133, v31, v23 offset0:2 offset1:3
	ds_write2_b32 v201, v32, v24 offset1:1
	ds_write2_b32 v201, v33, v25 offset0:2 offset1:3
	v_mul_f32_e32 v65, v59, v64
	v_mul_f32_e32 v67, v59, v66
	v_add_u32_e32 v14, v132, v127
	v_mul_f32_e32 v61, v59, v60
	v_mul_f32_e32 v63, v59, v62
	ds_write_b128 v14, v[64:67]
	ds_write_b128 v14, v[60:63] offset:16
	v_lshlrev_b64 v[14:15], 6, v[46:47]
	v_lshl_add_u64 v[14:15], s[12:13], 0, v[14:15]
	s_and_saveexec_b64 s[12:13], s[0:1]
	s_cbranch_execz .LBB0_192
	global_store_dword v[14:15], v58, off
.LBB0_192:
	s_or_b64 exec, exec, s[12:13]
	s_waitcnt vmcnt(1)
	v_lshlrev_b32_e32 v16, 16, v56
	s_waitcnt vmcnt(0)
	v_lshlrev_b32_e32 v20, 16, v52
	v_and_b32_e32 v21, 0xffff0000, v52
	v_exp_f32_e32 v18, v16
	v_lshlrev_b32_e32 v16, 16, v48
	v_and_b32_e32 v17, 0xffff0000, v48
	v_pk_fma_f32 v[22:23], v[20:21], v[2:3], v[38:39]
	v_lshlrev_b32_e32 v46, 16, v50
	v_and_b32_e32 v47, 0xffff0000, v50
	v_pk_mul_f32 v[22:23], v[22:23], v[16:17]
	v_pk_mul_f32 v[26:27], v[6:7], v[16:17]
	v_pk_mul_f32 v[16:17], v[22:23], v[46:47]
	v_lshlrev_b32_e32 v30, 16, v53
	v_and_b32_e32 v31, 0xffff0000, v53
	v_fma_f32 v16, v16, v10, 0
	v_lshlrev_b32_e32 v24, 16, v49
	v_and_b32_e32 v25, 0xffff0000, v49
	v_pk_fma_f32 v[32:33], v[30:31], v[4:5], v[40:41]
	v_pk_mul_f32 v[48:49], v[26:27], v[20:21]
	v_and_b32_e32 v19, 0xffff0000, v56
	v_fma_f32 v56, v26, v26, 0
	v_fma_f32 v58, v22, v46, 0
	v_fmac_f32_e32 v16, v17, v11
	v_lshlrev_b32_e32 v50, 16, v51
	v_and_b32_e32 v51, 0xffff0000, v51
	v_pk_mul_f32 v[28:29], v[8:9], v[24:25]
	v_pk_mul_f32 v[24:25], v[32:33], v[24:25]
	v_fma_f32 v17, v48, v46, 0
	v_fmac_f32_e32 v56, v27, v27
	v_fmac_f32_e32 v58, v23, v47
	v_pk_mul_f32 v[32:33], v[24:25], v[50:51]
	v_fmac_f32_e32 v17, v49, v47
	v_pk_mul_f32 v[30:31], v[28:29], v[30:31]
	v_fmac_f32_e32 v56, v28, v28
	v_fmac_f32_e32 v16, v32, v12
	v_fmac_f32_e32 v58, v24, v50
	v_fmac_f32_e32 v17, v30, v50
	v_fmac_f32_e32 v56, v29, v29
	v_fmac_f32_e32 v16, v33, v13
	v_fmac_f32_e32 v58, v25, v51
	v_fmac_f32_e32 v17, v31, v51
	s_nop 1
	v_add_f32_dpp v56, v56, v56 quad_perm:[1,0,3,2] row_mask:0xf bank_mask:0xf
	v_add_f32_dpp v16, v16, v16 quad_perm:[1,0,3,2] row_mask:0xf bank_mask:0xf
	v_add_f32_dpp v17, v17, v17 quad_perm:[1,0,3,2] row_mask:0xf bank_mask:0xf
	v_add_f32_dpp v58, v58, v58 quad_perm:[1,0,3,2] row_mask:0xf bank_mask:0xf
	v_add_f32_dpp v56, v56, v56 quad_perm:[2,3,0,1] row_mask:0xf bank_mask:0xf
	v_add_f32_dpp v16, v16, v16 quad_perm:[2,3,0,1] row_mask:0xf bank_mask:0xf
	v_add_f32_dpp v17, v17, v17 quad_perm:[2,3,0,1] row_mask:0xf bank_mask:0xf
	v_add_f32_dpp v58, v58, v58 quad_perm:[2,3,0,1] row_mask:0xf bank_mask:0xf
	v_add_f32_dpp v56, v56, v56 row_half_mirror row_mask:0xf bank_mask:0xf
	v_add_f32_dpp v16, v16, v16 row_half_mirror row_mask:0xf bank_mask:0xf
	v_add_f32_dpp v17, v17, v17 row_half_mirror row_mask:0xf bank_mask:0xf
	v_add_f32_dpp v58, v58, v58 row_half_mirror row_mask:0xf bank_mask:0xf
	v_add_f32_dpp v56, v56, v56 row_mirror row_mask:0xf bank_mask:0xf
	v_add_f32_dpp v16, v16, v16 row_mirror row_mask:0xf bank_mask:0xf
	v_add_f32_dpp v17, v17, v17 row_mirror row_mask:0xf bank_mask:0xf
	v_add_f32_dpp v58, v58, v58 row_mirror row_mask:0xf bank_mask:0xf
	s_nop 0
	v_lshlrev_b32_e32 v54, 16, v57
	v_max_f32_e32 v20, v56, v56
	v_and_b32_e32 v55, 0xffff0000, v57
	v_max_f32_e32 v20, 0x179abe15, v20
	v_rsq_f32_e32 v52, v20
	v_exp_f32_e32 v19, v19
	v_exp_f32_e32 v20, v54
	v_exp_f32_e32 v21, v55
	v_pk_mul_f32 v[26:27], v[26:27], v[52:53] op_sel_hi:[1,0]
	v_pk_mul_f32 v[28:29], v[28:29], v[52:53] op_sel_hi:[1,0]
	v_pk_mul_f32 v[32:33], v[30:31], v[52:53] op_sel_hi:[1,0]
	v_pk_mul_f32 v[30:31], v[48:49], v[52:53] op_sel_hi:[1,0]
	v_pk_mul_f32 v[46:47], v[18:19], v[46:47]
	v_pk_mul_f32 v[48:49], v[20:21], v[50:51]
	v_mul_f32_e64 v50, v17, -v52
	v_pk_fma_f32 v[48:49], v[50:51], v[28:29], v[48:49] op_sel_hi:[0,1,1]
	v_pk_fma_f32 v[46:47], v[50:51], v[26:27], v[46:47] op_sel_hi:[0,1,1]
	v_and_b32_e32 v52, 0xffff0000, v45
	v_lshlrev_b32_e32 v50, 16, v45
	v_and_b32_e32 v56, 0xffff0000, v44
	v_lshlrev_b32_e32 v54, 16, v44
	v_mul_f32_e32 v55, v58, v54
	v_mul_f32_e32 v57, v58, v56
	v_add_u32_e32 v17, v132, v130
	v_mul_f32_e32 v51, v58, v50
	v_mul_f32_e32 v53, v58, v52
	ds_write_b128 v134, v[30:33] offset:32768
	ds_write_b128 v134, v[22:25] offset:16384
	ds_write_b128 v134, v[18:21] offset:24576
	v_add_u32_e32 v201, 0x2000, v134
	ds_write2_b32 v134, v26, v46 offset1:1
	ds_write2_b32 v134, v27, v47 offset0:2 offset1:3
	ds_write2_b32 v201, v28, v48 offset1:1
	ds_write2_b32 v201, v29, v49 offset0:2 offset1:3
	ds_write_b128 v17, v[54:57]
	ds_write_b128 v17, v[50:53] offset:16
	s_and_saveexec_b64 s[12:13], s[0:1]
	s_cbranch_execz .LBB0_194
	global_store_dword v[14:15], v16, off offset:1024

.LBB0_197:
	s_andn2_b32 s2, 0x400, s13
	v_lshl_add_u32 v48, s2, 2, v131
	v_readlane_b32 s20, v248, 7
	ds_read_b128 v[48:51], v48
	v_readlane_b32 s21, v248, 8
	s_waitcnt lgkmcnt(0)
	v_cvt_pk_bf16_f32 v48, v48, v49
	v_cvt_pk_bf16_f32 v49, v50, v51
	s_cmp_eq_u32 s12, 64
	v_readlane_b32 s22, v248, 9
	v_lshl_add_u64 v[50:51], s[20:21], 0, v[18:19]
	v_readlane_b32 s23, v248, 10
	global_store_dwordx2 v[50:51], v[48:49], off
	s_cbranch_scc1 .LBB0_196
	s_waitcnt vmcnt(7)
	v_lshlrev_b32_e32 v60, 16, v44
	v_and_b32_e32 v61, 0xffff0000, v44
	v_lshlrev_b32_e32 v52, 16, v32
	v_and_b32_e32 v53, 0xffff0000, v32
	v_pk_fma_f32 v[54:55], v[60:61], v[2:3], v[38:39]
	v_lshlrev_b32_e32 v50, 16, v46
	v_and_b32_e32 v51, 0xffff0000, v46
	v_lshlrev_b32_e32 v69, 16, v47
	v_and_b32_e32 v70, 0xffff0000, v47
	v_lshlrev_b32_e32 v46, 16, v42
	v_and_b32_e32 v47, 0xffff0000, v42
	v_pk_mul_f32 v[54:55], v[54:55], v[52:53]
	v_pk_mul_f32 v[58:59], v[6:7], v[52:53]
	v_pk_mul_f32 v[52:53], v[54:55], v[46:47]
	v_lshlrev_b32_e32 v44, 16, v45
	v_fma_f32 v32, v52, v10, 0
	v_and_b32_e32 v45, 0xffff0000, v45
	v_fmac_f32_e32 v32, v53, v11
	v_lshlrev_b32_e32 v62, 16, v43
	v_and_b32_e32 v63, 0xffff0000, v43
	v_lshlrev_b32_e32 v42, 16, v33
	v_and_b32_e32 v43, 0xffff0000, v33
	v_pk_fma_f32 v[52:53], v[44:45], v[4:5], v[40:41]
	v_pk_mul_f32 v[66:67], v[58:59], v[60:61]
	v_fma_f32 v68, v58, v58, 0
	v_fma_f32 v74, v54, v46, 0
	v_pk_mul_f32 v[64:65], v[8:9], v[42:43]
	v_pk_mul_f32 v[56:57], v[52:53], v[42:43]
	v_fma_f32 v33, v66, v46, 0
	v_fmac_f32_e32 v68, v59, v59
	v_fmac_f32_e32 v74, v55, v47
	v_pk_mul_f32 v[42:43], v[56:57], v[62:63]
	v_fmac_f32_e32 v33, v67, v47
	v_pk_mul_f32 v[60:61], v[64:65], v[44:45]
	v_fmac_f32_e32 v68, v64, v64
	v_fmac_f32_e32 v32, v42, v12
	v_fmac_f32_e32 v74, v56, v62
	v_fmac_f32_e32 v33, v60, v62
	v_fmac_f32_e32 v68, v65, v65
	v_fmac_f32_e32 v32, v43, v13
	v_fmac_f32_e32 v74, v57, v63
	v_fmac_f32_e32 v33, v61, v63
	s_nop 1
	v_add_f32_dpp v68, v68, v68 quad_perm:[1,0,3,2] row_mask:0xf bank_mask:0xf
	v_add_f32_dpp v32, v32, v32 quad_perm:[1,0,3,2] row_mask:0xf bank_mask:0xf
	v_add_f32_dpp v33, v33, v33 quad_perm:[1,0,3,2] row_mask:0xf bank_mask:0xf
	v_add_f32_dpp v74, v74, v74 quad_perm:[1,0,3,2] row_mask:0xf bank_mask:0xf
	v_add_f32_dpp v68, v68, v68 quad_perm:[2,3,0,1] row_mask:0xf bank_mask:0xf
	v_add_f32_dpp v32, v32, v32 quad_perm:[2,3,0,1] row_mask:0xf bank_mask:0xf
	v_add_f32_dpp v33, v33, v33 quad_perm:[2,3,0,1] row_mask:0xf bank_mask:0xf
	v_add_f32_dpp v74, v74, v74 quad_perm:[2,3,0,1] row_mask:0xf bank_mask:0xf
	v_add_f32_dpp v68, v68, v68 row_half_mirror row_mask:0xf bank_mask:0xf
	v_add_f32_dpp v32, v32, v32 row_half_mirror row_mask:0xf bank_mask:0xf
	v_add_f32_dpp v33, v33, v33 row_half_mirror row_mask:0xf bank_mask:0xf
	v_add_f32_dpp v74, v74, v74 row_half_mirror row_mask:0xf bank_mask:0xf
	v_add_f32_dpp v68, v68, v68 row_mirror row_mask:0xf bank_mask:0xf
	v_add_f32_dpp v32, v32, v32 row_mirror row_mask:0xf bank_mask:0xf
	v_add_f32_dpp v33, v33, v33 row_mirror row_mask:0xf bank_mask:0xf
	v_add_f32_dpp v74, v74, v74 row_mirror row_mask:0xf bank_mask:0xf
	s_nop 0
	v_exp_f32_e32 v50, v50
	v_max_f32_e32 v42, v68, v68
	v_max_f32_e32 v42, 0x179abe15, v42
	v_rsq_f32_e32 v68, v42
	v_exp_f32_e32 v51, v51
	v_exp_f32_e32 v52, v69
	v_exp_f32_e32 v53, v70
	s_bitcmp1_b32 s12, 0
	s_cselect_b32 s2, 0xe000, 0
	v_readlane_b32 s3, v251, 27
	s_add_i32 s2, s3, s2
	v_add_u32_e32 v49, s2, v122
	v_pk_mul_f32 v[42:43], v[58:59], v[68:69] op_sel_hi:[1,0]
	v_pk_mul_f32 v[44:45], v[64:65], v[68:69] op_sel_hi:[1,0]
	v_pk_mul_f32 v[58:59], v[66:67], v[68:69] op_sel_hi:[1,0]
	v_pk_mul_f32 v[46:47], v[50:51], v[46:47]
	v_pk_mul_f32 v[62:63], v[52:53], v[62:63]
	v_mul_f32_e64 v66, v33, -v68
	v_add_u32_e32 v48, s2, v123
	v_pk_mul_f32 v[60:61], v[60:61], v[68:69] op_sel_hi:[1,0]
	v_pk_fma_f32 v[64:65], v[66:67], v[44:45], v[62:63] op_sel_hi:[0,1,1]
	v_pk_fma_f32 v[62:63], v[66:67], v[42:43], v[46:47] op_sel_hi:[0,1,1]
	s_waitcnt vmcnt(4)
	v_and_b32_e32 v68, 0xffff0000, v31
	v_lshlrev_b32_e32 v66, 16, v31
	v_and_b32_e32 v72, 0xffff0000, v30
	v_lshlrev_b32_e32 v70, 16, v30
	v_add_u32_e32 v30, v49, v125
	ds_write_b128 v30, v[58:61] offset:32768
	ds_write_b128 v30, v[54:57] offset:16384
	ds_write_b128 v30, v[50:53] offset:24576
	v_add_u32_e32 v201, 0x2000, v30
	ds_write2_b32 v30, v42, v62 offset1:1
	ds_write2_b32 v30, v43, v63 offset0:2 offset1:3
	ds_write2_b32 v201, v44, v64 offset1:1
	ds_write2_b32 v201, v45, v65 offset0:2 offset1:3
	v_add_u32_e32 v30, v48, v127
	v_mul_f32_e32 v71, v74, v70
	v_mul_f32_e32 v73, v74, v72
	v_mul_f32_e32 v67, v74, v66
	v_mul_f32_e32 v69, v74, v68
	ds_write_b128 v30, v[70:73] offset:40960
	ds_write_b128 v30, v[66:69] offset:40976
	v_lshl_add_u64 v[30:31], s[20:21], 0, v[16:17]
	s_and_saveexec_b64 s[2:3], s[0:1]
	s_cbranch_execz .LBB0_200
	v_add_co_u32_e32 v42, vcc, 0x15d01000, v30
	s_nop 1
	v_addc_co_u32_e32 v43, vcc, 0, v31, vcc
	global_store_dword v[42:43], v32, off
.LBB0_200:
	s_or_b64 exec, exec, s[2:3]
	s_waitcnt vmcnt(2)
	v_lshlrev_b32_e32 v32, 16, v28
	s_waitcnt vmcnt(1)
	v_lshlrev_b32_e32 v44, 16, v26
	v_and_b32_e32 v45, 0xffff0000, v26
	v_exp_f32_e32 v42, v32
	v_lshlrev_b32_e32 v32, 16, v24
	v_and_b32_e32 v33, 0xffff0000, v24
	v_pk_fma_f32 v[50:51], v[44:45], v[2:3], v[38:39]
	v_and_b32_e32 v43, 0xffff0000, v28
	v_lshlrev_b32_e32 v61, 16, v29
	v_and_b32_e32 v62, 0xffff0000, v29
	v_lshlrev_b32_e32 v28, 16, v22
	v_and_b32_e32 v29, 0xffff0000, v22
	v_pk_mul_f32 v[50:51], v[50:51], v[32:33]
	v_pk_mul_f32 v[46:47], v[6:7], v[32:33]
	v_pk_mul_f32 v[32:33], v[50:51], v[28:29]
	v_lshlrev_b32_e32 v26, 16, v27
	v_and_b32_e32 v27, 0xffff0000, v27
	v_fma_f32 v22, v32, v10, 0
	v_lshlrev_b32_e32 v24, 16, v25
	v_and_b32_e32 v25, 0xffff0000, v25
	v_pk_fma_f32 v[52:53], v[26:27], v[4:5], v[40:41]
	v_pk_mul_f32 v[58:59], v[46:47], v[44:45]
	v_fma_f32 v60, v46, v46, 0
	v_fma_f32 v65, v50, v28, 0
	v_fmac_f32_e32 v22, v33, v11
	v_lshlrev_b32_e32 v32, 16, v23
	v_and_b32_e32 v33, 0xffff0000, v23
	v_pk_mul_f32 v[54:55], v[8:9], v[24:25]
	v_pk_mul_f32 v[52:53], v[52:53], v[24:25]
	v_fma_f32 v23, v58, v28, 0
	v_fmac_f32_e32 v60, v47, v47
	v_fmac_f32_e32 v65, v51, v29
	v_pk_mul_f32 v[24:25], v[52:53], v[32:33]
	v_fmac_f32_e32 v23, v59, v29
	v_pk_mul_f32 v[56:57], v[54:55], v[26:27]
	v_fmac_f32_e32 v60, v54, v54
	v_fmac_f32_e32 v22, v24, v12
	v_fmac_f32_e32 v65, v52, v32
	v_fmac_f32_e32 v23, v56, v32
	v_fmac_f32_e32 v60, v55, v55
	v_fmac_f32_e32 v22, v25, v13
	v_fmac_f32_e32 v65, v53, v33
	v_fmac_f32_e32 v23, v57, v33
	s_nop 1
	v_add_f32_dpp v60, v60, v60 quad_perm:[1,0,3,2] row_mask:0xf bank_mask:0xf
	v_add_f32_dpp v22, v22, v22 quad_perm:[1,0,3,2] row_mask:0xf bank_mask:0xf
	v_add_f32_dpp v23, v23, v23 quad_perm:[1,0,3,2] row_mask:0xf bank_mask:0xf
	v_add_f32_dpp v65, v65, v65 quad_perm:[1,0,3,2] row_mask:0xf bank_mask:0xf
	v_add_f32_dpp v60, v60, v60 quad_perm:[2,3,0,1] row_mask:0xf bank_mask:0xf
	v_add_f32_dpp v22, v22, v22 quad_perm:[2,3,0,1] row_mask:0xf bank_mask:0xf
	v_add_f32_dpp v23, v23, v23 quad_perm:[2,3,0,1] row_mask:0xf bank_mask:0xf
	v_add_f32_dpp v65, v65, v65 quad_perm:[2,3,0,1] row_mask:0xf bank_mask:0xf
	v_add_f32_dpp v60, v60, v60 row_half_mirror row_mask:0xf bank_mask:0xf
	v_add_f32_dpp v22, v22, v22 row_half_mirror row_mask:0xf bank_mask:0xf
	v_add_f32_dpp v23, v23, v23 row_half_mirror row_mask:0xf bank_mask:0xf
	v_add_f32_dpp v65, v65, v65 row_half_mirror row_mask:0xf bank_mask:0xf
	v_add_f32_dpp v60, v60, v60 row_mirror row_mask:0xf bank_mask:0xf
	v_add_f32_dpp v22, v22, v22 row_mirror row_mask:0xf bank_mask:0xf
	v_add_f32_dpp v23, v23, v23 row_mirror row_mask:0xf bank_mask:0xf
	v_add_f32_dpp v65, v65, v65 row_mirror row_mask:0xf bank_mask:0xf
	s_nop 0
	v_exp_f32_e32 v43, v43
	v_max_f32_e32 v24, v60, v60
	v_max_f32_e32 v24, 0x179abe15, v24
	v_rsq_f32_e32 v60, v24
	v_exp_f32_e32 v44, v61
	v_exp_f32_e32 v45, v62
	v_pk_mul_f32 v[28:29], v[42:43], v[28:29]
	v_pk_mul_f32 v[24:25], v[46:47], v[60:61] op_sel_hi:[1,0]
	v_pk_mul_f32 v[26:27], v[54:55], v[60:61] op_sel_hi:[1,0]
	v_pk_mul_f32 v[32:33], v[44:45], v[32:33]
	v_mul_f32_e64 v46, v23, -v60
	v_and_b32_e32 v64, 0xffff0000, v21
	v_lshlrev_b32_e32 v62, 16, v21
	v_and_b32_e32 v68, 0xffff0000, v20
	v_lshlrev_b32_e32 v66, 16, v20
	v_add_u32_e32 v20, v49, v128
	v_pk_mul_f32 v[56:57], v[56:57], v[60:61] op_sel_hi:[1,0]
	v_pk_mul_f32 v[54:55], v[58:59], v[60:61] op_sel_hi:[1,0]
	v_pk_fma_f32 v[60:61], v[46:47], v[26:27], v[32:33] op_sel_hi:[0,1,1]
	v_pk_fma_f32 v[58:59], v[46:47], v[24:25], v[28:29] op_sel_hi:[0,1,1]
	ds_write_b128 v20, v[54:57] offset:32768
	ds_write_b128 v20, v[50:53] offset:16384
	ds_write_b128 v20, v[42:45] offset:24576
	v_add_u32_e32 v201, 0x2000, v20
	ds_write2_b32 v20, v24, v58 offset1:1
	ds_write2_b32 v20, v25, v59 offset0:2 offset1:3
	ds_write2_b32 v201, v26, v60 offset1:1
	ds_write2_b32 v201, v27, v61 offset0:2 offset1:3
	v_add_u32_e32 v20, v48, v130
	v_mul_f32_e32 v67, v65, v66
	v_mul_f32_e32 v69, v65, v68
	v_mul_f32_e32 v63, v65, v62
	v_mul_f32_e32 v65, v65, v64
	ds_write_b128 v20, v[66:69] offset:40960
	ds_write_b128 v20, v[62:65] offset:40976
	s_and_saveexec_b64 s[2:3], s[0:1]
	s_cbranch_execz .LBB0_195
	v_add_co_u32_e32 v20, vcc, 0x15d01000, v30
	s_nop 1
	v_addc_co_u32_e32 v21, vcc, 0, v31, vcc
	global_store_dword v[20:21], v22, off offset:1024
	s_branch .LBB0_195

.LBB0_203:
	s_andn2_saveexec_b64 s[0:1], s[8:9]
	s_cbranch_execz .LBB0_184
	s_waitcnt lgkmcnt(0)
	s_barrier
	v_readlane_b32 s2, v251, 27
	v_and_b32_e32 v78, 15, v0
	v_lshrrev_b32_e32 v79, 4, v0
	s_nop 1
	v_lshl_add_u32 v103, v78, 4, s2
	v_lshl_add_u32 v38, v78, 5, s2
	v_bfe_u32 v81, v78, 2, 1
	v_lshlrev_b32_e32 v80, 1, v79
	v_add_u32_e32 v80, v80, v81
	v_lshl_add_u32 v77, s17, 5, v80
	v_xor_b32_e32 v40, 1, v77
	v_lshl_add_u32 v75, v77, 3, s2
	v_add_u32_e32 v75, 0xa000, v75
	v_lshl_add_u32 v37, v40, 3, s2
	v_add_u32_e32 v37, 0xa000, v37
	v_lshl_add_u32 v80, v80, 2, s2
	v_add_u32_e32 v80, 0x1c000, v80
	v_lshl_add_u32 v79, v0, 2, s2
	v_add_u32_e32 v79, 0x1e000, v79
	v_and_b32_e32 v81, 11, v78
	v_cmp_eq_u32_e32 vcc, 0, v81
	s_nop 3
	v_cndmask_b32_e32 v76, v79, v80, vcc
	v_mov_b32_e32 v20, 0
	v_mov_b32_e32 v21, 0
	v_mov_b32_e32 v22, 0
	v_mov_b32_e32 v23, 0
	v_mov_b32_e32 v24, 0
	v_mov_b32_e32 v25, 0
	v_mov_b32_e32 v26, 0
	v_mov_b32_e32 v27, 0
	s_setprio 3
	s_mov_b32 s8, 0
	s_waitcnt vmcnt(0)
.Lrw_scan_loop:
	s_and_b32 s2, s8, 1
	s_mul_i32 s3, s2, 0xe000
	s_lshl_b32 s2, s2, 12
	v_add_u32_e32 v195, s3, v103
	v_add_u32_e32 v33, s3, v38
	v_add_u32_e32 v196, s3, v75
	v_add_u32_e32 v36, s3, v37
	v_add_u32_e32 v102, s2, v76
	ds_read_b128 v[140:143], v195 offset:0
	ds_read_b128 v[152:155], v195 offset:8192
	ds_read_b128 v[164:167], v195 offset:24576
	ds_read_b128 v[176:179], v195 offset:16384
	ds_read_b128 v[84:87], v195 offset:32768
	ds_read_b64 v[4:5], v196 offset:0
	ds_read_b64 v[6:7], v36 offset:0
	ds_read_b128 v[144:147], v195 offset:256
	ds_read_b128 v[156:159], v195 offset:8448
	ds_read_b128 v[168:171], v195 offset:24832
	ds_read_b128 v[180:183], v195 offset:16640
	ds_read_b128 v[88:91], v195 offset:33024
	ds_read_b64 v[8:9], v196 offset:512
	ds_read_b64 v[10:11], v36 offset:512
	ds_read_b128 v[148:151], v195 offset:512
	ds_read_b128 v[160:163], v195 offset:8704
	ds_read_b128 v[172:175], v195 offset:25088
	ds_read_b128 v[184:187], v195 offset:16896
	ds_read_b128 v[92:95], v195 offset:33280
	ds_read_b64 v[12:13], v196 offset:1024
	ds_read_b64 v[14:15], v36 offset:1024
	s_waitcnt lgkmcnt(14)
	v_pk_mul_f32 v[46:47], v[24:25], v[140:141] op_sel_hi:[0,1]
	v_pk_mul_f32 v[34:35], v[20:21], v[140:141] op_sel_hi:[0,1]
	v_pk_fma_f32 v[46:47], v[24:25], v[142:143], v[46:47] op_sel:[1,0,0] op_sel_hi:[1,1,1]
	v_pk_fma_f32 v[34:35], v[20:21], v[142:143], v[34:35] op_sel:[1,0,0] op_sel_hi:[1,1,1]
	v_pk_fma_f32 v[46:47], v[26:27], v[152:153], v[46:47] op_sel_hi:[0,1,1]
	v_pk_fma_f32 v[34:35], v[22:23], v[152:153], v[34:35] op_sel_hi:[0,1,1]
	v_pk_fma_f32 v[46:47], v[26:27], v[154:155], v[46:47] op_sel:[1,0,0] op_sel_hi:[1,1,1]
	v_pk_fma_f32 v[34:35], v[22:23], v[154:155], v[34:35] op_sel:[1,0,0] op_sel_hi:[1,1,1]
	v_pk_mul_f32 v[20:21], v[20:21], v[164:165]
	v_add_f32_dpp v28, v46, v34 row_half_mirror row_mask:0xf bank_mask:0xf
	v_add_f32_dpp v32, v47, v35 row_half_mirror row_mask:0xf bank_mask:0xf
	v_pk_mul_f32 v[22:23], v[22:23], v[166:167]
	v_add_f32_dpp v28, v28, v28 row_ror:8 row_mask:0xf bank_mask:0xf
	v_add_f32_dpp v32, v32, v32 row_ror:8 row_mask:0xf bank_mask:0xf
	v_pk_mul_f32 v[24:25], v[24:25], v[164:165]
	v_add_f32_dpp v28, v28, v28 quad_perm:[1,0,3,2] row_mask:0xf bank_mask:0xf
	v_add_f32_dpp v32, v32, v32 quad_perm:[1,0,3,2] row_mask:0xf bank_mask:0xf
	v_pk_mul_f32 v[26:27], v[26:27], v[166:167]
	v_add_f32_dpp v28, v28, v28 quad_perm:[2,3,0,1] row_mask:0xf bank_mask:0xf
	v_add_f32_dpp v32, v32, v32 quad_perm:[2,3,0,1] row_mask:0xf bank_mask:0xf
	v_pk_fma_f32 v[20:21], v[176:177], v[4:5], v[20:21] op_sel_hi:[1,0,1]
	v_mov_b32_dpp v30, v28 row_half_mirror row_mask:0xf bank_mask:0xf
	v_pk_fma_f32 v[22:23], v[178:179], v[4:5], v[22:23] op_sel_hi:[1,0,1]
	v_pk_fma_f32 v[24:25], v[176:177], v[6:7], v[24:25] op_sel_hi:[1,0,1]
	v_pk_fma_f32 v[26:27], v[178:179], v[6:7], v[26:27] op_sel_hi:[1,0,1]
	v_pk_fma_f32 v[20:21], v[84:85], v[28:29], v[20:21] op_sel_hi:[1,0,1] neg_lo:[0,1,0] neg_hi:[0,1,0]
	v_pk_fma_f32 v[22:23], v[86:87], v[28:29], v[22:23] op_sel_hi:[1,0,1] neg_lo:[0,1,0] neg_hi:[0,1,0]
	v_pk_fma_f32 v[24:25], v[84:85], v[30:31], v[24:25] op_sel_hi:[1,0,1] neg_lo:[0,1,0] neg_hi:[0,1,0]
	v_pk_fma_f32 v[26:27], v[86:87], v[30:31], v[26:27] op_sel_hi:[1,0,1] neg_lo:[0,1,0] neg_hi:[0,1,0]
	v_add_f32_e32 v39, v32, v5
	ds_write_b32 v102, v39 offset:0
	ds_read_b128 v[140:143], v195 offset:768
	ds_read_b128 v[152:155], v195 offset:8960
	ds_read_b128 v[164:167], v195 offset:25344
	ds_read_b128 v[176:179], v195 offset:17152
	ds_read_b128 v[84:87], v195 offset:33536
	ds_read_b64 v[4:5], v196 offset:1536
	ds_read_b64 v[6:7], v36 offset:1536
	s_waitcnt lgkmcnt(15)
	v_pk_mul_f32 v[46:47], v[24:25], v[144:145] op_sel_hi:[0,1]
	v_pk_mul_f32 v[34:35], v[20:21], v[144:145] op_sel_hi:[0,1]
	v_pk_fma_f32 v[46:47], v[24:25], v[146:147], v[46:47] op_sel:[1,0,0] op_sel_hi:[1,1,1]
	v_pk_fma_f32 v[34:35], v[20:21], v[146:147], v[34:35] op_sel:[1,0,0] op_sel_hi:[1,1,1]
	v_pk_fma_f32 v[46:47], v[26:27], v[156:157], v[46:47] op_sel_hi:[0,1,1]
	v_pk_fma_f32 v[34:35], v[22:23], v[156:157], v[34:35] op_sel_hi:[0,1,1]
	v_pk_fma_f32 v[46:47], v[26:27], v[158:159], v[46:47] op_sel:[1,0,0] op_sel_hi:[1,1,1]
	v_pk_fma_f32 v[34:35], v[22:23], v[158:159], v[34:35] op_sel:[1,0,0] op_sel_hi:[1,1,1]
	v_pk_mul_f32 v[20:21], v[20:21], v[168:169]
	v_add_f32_dpp v28, v46, v34 row_half_mirror row_mask:0xf bank_mask:0xf
	v_add_f32_dpp v32, v47, v35 row_half_mirror row_mask:0xf bank_mask:0xf
	v_pk_mul_f32 v[22:23], v[22:23], v[170:171]
	v_add_f32_dpp v28, v28, v28 row_ror:8 row_mask:0xf bank_mask:0xf
	v_add_f32_dpp v32, v32, v32 row_ror:8 row_mask:0xf bank_mask:0xf
	v_pk_mul_f32 v[24:25], v[24:25], v[168:169]
	v_add_f32_dpp v28, v28, v28 quad_perm:[1,0,3,2] row_mask:0xf bank_mask:0xf
	v_add_f32_dpp v32, v32, v32 quad_perm:[1,0,3,2] row_mask:0xf bank_mask:0xf
	v_pk_mul_f32 v[26:27], v[26:27], v[170:171]
	v_add_f32_dpp v28, v28, v28 quad_perm:[2,3,0,1] row_mask:0xf bank_mask:0xf
	v_add_f32_dpp v32, v32, v32 quad_perm:[2,3,0,1] row_mask:0xf bank_mask:0xf
	v_pk_fma_f32 v[20:21], v[180:181], v[8:9], v[20:21] op_sel_hi:[1,0,1]
	v_mov_b32_dpp v30, v28 row_half_mirror row_mask:0xf bank_mask:0xf
	v_pk_fma_f32 v[22:23], v[182:183], v[8:9], v[22:23] op_sel_hi:[1,0,1]
	v_pk_fma_f32 v[24:25], v[180:181], v[10:11], v[24:25] op_sel_hi:[1,0,1]
	v_pk_fma_f32 v[26:27], v[182:183], v[10:11], v[26:27] op_sel_hi:[1,0,1]
	v_pk_fma_f32 v[20:21], v[88:89], v[28:29], v[20:21] op_sel_hi:[1,0,1] neg_lo:[0,1,0] neg_hi:[0,1,0]
	v_pk_fma_f32 v[22:23], v[90:91], v[28:29], v[22:23] op_sel_hi:[1,0,1] neg_lo:[0,1,0] neg_hi:[0,1,0]
	v_pk_fma_f32 v[24:25], v[88:89], v[30:31], v[24:25] op_sel_hi:[1,0,1] neg_lo:[0,1,0] neg_hi:[0,1,0]
	v_pk_fma_f32 v[26:27], v[90:91], v[30:31], v[26:27] op_sel_hi:[1,0,1] neg_lo:[0,1,0] neg_hi:[0,1,0]
	v_add_f32_e32 v39, v32, v9
	ds_write_b32 v102, v39 offset:128
	ds_read_b128 v[144:147], v195 offset:1024
	ds_read_b128 v[156:159], v195 offset:9216
	ds_read_b128 v[168:171], v195 offset:25600
	ds_read_b128 v[180:183], v195 offset:17408
	ds_read_b128 v[88:91], v195 offset:33792
	ds_read_b64 v[8:9], v196 offset:2048
	ds_read_b64 v[10:11], v36 offset:2048
	s_waitcnt lgkmcnt(15)
	v_pk_mul_f32 v[46:47], v[24:25], v[148:149] op_sel_hi:[0,1]
	v_pk_mul_f32 v[34:35], v[20:21], v[148:149] op_sel_hi:[0,1]
	v_pk_fma_f32 v[46:47], v[24:25], v[150:151], v[46:47] op_sel:[1,0,0] op_sel_hi:[1,1,1]
	v_pk_fma_f32 v[34:35], v[20:21], v[150:151], v[34:35] op_sel:[1,0,0] op_sel_hi:[1,1,1]
	v_pk_fma_f32 v[46:47], v[26:27], v[160:161], v[46:47] op_sel_hi:[0,1,1]
	v_pk_fma_f32 v[34:35], v[22:23], v[160:161], v[34:35] op_sel_hi:[0,1,1]
	v_pk_fma_f32 v[46:47], v[26:27], v[162:163], v[46:47] op_sel:[1,0,0] op_sel_hi:[1,1,1]
	v_pk_fma_f32 v[34:35], v[22:23], v[162:163], v[34:35] op_sel:[1,0,0] op_sel_hi:[1,1,1]
	v_pk_mul_f32 v[20:21], v[20:21], v[172:173]
	v_add_f32_dpp v28, v46, v34 row_half_mirror row_mask:0xf bank_mask:0xf
	v_add_f32_dpp v32, v47, v35 row_half_mirror row_mask:0xf bank_mask:0xf
	v_pk_mul_f32 v[22:23], v[22:23], v[174:175]
	v_add_f32_dpp v28, v28, v28 row_ror:8 row_mask:0xf bank_mask:0xf
	v_add_f32_dpp v32, v32, v32 row_ror:8 row_mask:0xf bank_mask:0xf
	v_pk_mul_f32 v[24:25], v[24:25], v[172:173]
	v_add_f32_dpp v28, v28, v28 quad_perm:[1,0,3,2] row_mask:0xf bank_mask:0xf
	v_add_f32_dpp v32, v32, v32 quad_perm:[1,0,3,2] row_mask:0xf bank_mask:0xf
	v_pk_mul_f32 v[26:27], v[26:27], v[174:175]
	v_add_f32_dpp v28, v28, v28 quad_perm:[2,3,0,1] row_mask:0xf bank_mask:0xf
	v_add_f32_dpp v32, v32, v32 quad_perm:[2,3,0,1] row_mask:0xf bank_mask:0xf
	v_pk_fma_f32 v[20:21], v[184:185], v[12:13], v[20:21] op_sel_hi:[1,0,1]
	v_mov_b32_dpp v30, v28 row_half_mirror row_mask:0xf bank_mask:0xf
	v_pk_fma_f32 v[22:23], v[186:187], v[12:13], v[22:23] op_sel_hi:[1,0,1]
	v_pk_fma_f32 v[24:25], v[184:185], v[14:15], v[24:25] op_sel_hi:[1,0,1]
	v_pk_fma_f32 v[26:27], v[186:187], v[14:15], v[26:27] op_sel_hi:[1,0,1]
	v_pk_fma_f32 v[20:21], v[92:93], v[28:29], v[20:21] op_sel_hi:[1,0,1] neg_lo:[0,1,0] neg_hi:[0,1,0]
	v_pk_fma_f32 v[22:23], v[94:95], v[28:29], v[22:23] op_sel_hi:[1,0,1] neg_lo:[0,1,0] neg_hi:[0,1,0]
	v_pk_fma_f32 v[24:25], v[92:93], v[30:31], v[24:25] op_sel_hi:[1,0,1] neg_lo:[0,1,0] neg_hi:[0,1,0]
	v_pk_fma_f32 v[26:27], v[94:95], v[30:31], v[26:27] op_sel_hi:[1,0,1] neg_lo:[0,1,0] neg_hi:[0,1,0]
	v_add_f32_e32 v39, v32, v13
	ds_write_b32 v102, v39 offset:256
	ds_read_b128 v[148:151], v195 offset:1280
	ds_read_b128 v[160:163], v195 offset:9472
	ds_read_b128 v[172:175], v195 offset:25856
	ds_read_b128 v[184:187], v195 offset:17664
	ds_read_b128 v[92:95], v195 offset:34048
	ds_read_b64 v[12:13], v196 offset:2560
	ds_read_b64 v[14:15], v36 offset:2560
	s_waitcnt lgkmcnt(15)
	v_pk_mul_f32 v[46:47], v[24:25], v[140:141] op_sel_hi:[0,1]
	v_pk_mul_f32 v[34:35], v[20:21], v[140:141] op_sel_hi:[0,1]
	v_pk_fma_f32 v[46:47], v[24:25], v[142:143], v[46:47] op_sel:[1,0,0] op_sel_hi:[1,1,1]
	v_pk_fma_f32 v[34:35], v[20:21], v[142:143], v[34:35] op_sel:[1,0,0] op_sel_hi:[1,1,1]
	v_pk_fma_f32 v[46:47], v[26:27], v[152:153], v[46:47] op_sel_hi:[0,1,1]
	v_pk_fma_f32 v[34:35], v[22:23], v[152:153], v[34:35] op_sel_hi:[0,1,1]
	v_pk_fma_f32 v[46:47], v[26:27], v[154:155], v[46:47] op_sel:[1,0,0] op_sel_hi:[1,1,1]
	v_pk_fma_f32 v[34:35], v[22:23], v[154:155], v[34:35] op_sel:[1,0,0] op_sel_hi:[1,1,1]
	v_pk_mul_f32 v[20:21], v[20:21], v[164:165]
	v_add_f32_dpp v28, v46, v34 row_half_mirror row_mask:0xf bank_mask:0xf
	v_add_f32_dpp v32, v47, v35 row_half_mirror row_mask:0xf bank_mask:0xf
	v_pk_mul_f32 v[22:23], v[22:23], v[166:167]
	v_add_f32_dpp v28, v28, v28 row_ror:8 row_mask:0xf bank_mask:0xf
	v_add_f32_dpp v32, v32, v32 row_ror:8 row_mask:0xf bank_mask:0xf
	v_pk_mul_f32 v[24:25], v[24:25], v[164:165]
	v_add_f32_dpp v28, v28, v28 quad_perm:[1,0,3,2] row_mask:0xf bank_mask:0xf
	v_add_f32_dpp v32, v32, v32 quad_perm:[1,0,3,2] row_mask:0xf bank_mask:0xf
	v_pk_mul_f32 v[26:27], v[26:27], v[166:167]
	v_add_f32_dpp v28, v28, v28 quad_perm:[2,3,0,1] row_mask:0xf bank_mask:0xf
	v_add_f32_dpp v32, v32, v32 quad_perm:[2,3,0,1] row_mask:0xf bank_mask:0xf
	v_pk_fma_f32 v[20:21], v[176:177], v[4:5], v[20:21] op_sel_hi:[1,0,1]
	v_mov_b32_dpp v30, v28 row_half_mirror row_mask:0xf bank_mask:0xf
	v_pk_fma_f32 v[22:23], v[178:179], v[4:5], v[22:23] op_sel_hi:[1,0,1]
	v_pk_fma_f32 v[24:25], v[176:177], v[6:7], v[24:25] op_sel_hi:[1,0,1]
	v_pk_fma_f32 v[26:27], v[178:179], v[6:7], v[26:27] op_sel_hi:[1,0,1]
	v_pk_fma_f32 v[20:21], v[84:85], v[28:29], v[20:21] op_sel_hi:[1,0,1] neg_lo:[0,1,0] neg_hi:[0,1,0]
	v_pk_fma_f32 v[22:23], v[86:87], v[28:29], v[22:23] op_sel_hi:[1,0,1] neg_lo:[0,1,0] neg_hi:[0,1,0]
	v_pk_fma_f32 v[24:25], v[84:85], v[30:31], v[24:25] op_sel_hi:[1,0,1] neg_lo:[0,1,0] neg_hi:[0,1,0]
	v_pk_fma_f32 v[26:27], v[86:87], v[30:31], v[26:27] op_sel_hi:[1,0,1] neg_lo:[0,1,0] neg_hi:[0,1,0]
	v_add_f32_e32 v39, v32, v5
	ds_write_b32 v102, v39 offset:384
	ds_read_b128 v[140:143], v195 offset:1536
	ds_read_b128 v[152:155], v195 offset:9728
	ds_read_b128 v[164:167], v195 offset:26112
	ds_read_b128 v[176:179], v195 offset:17920
	ds_read_b128 v[84:87], v195 offset:34304
	ds_read_b64 v[4:5], v196 offset:3072
	ds_read_b64 v[6:7], v36 offset:3072
	s_waitcnt lgkmcnt(15)
	v_pk_mul_f32 v[46:47], v[24:25], v[144:145] op_sel_hi:[0,1]
	v_pk_mul_f32 v[34:35], v[20:21], v[144:145] op_sel_hi:[0,1]
	v_pk_fma_f32 v[46:47], v[24:25], v[146:147], v[46:47] op_sel:[1,0,0] op_sel_hi:[1,1,1]
	v_pk_fma_f32 v[34:35], v[20:21], v[146:147], v[34:35] op_sel:[1,0,0] op_sel_hi:[1,1,1]
	v_pk_fma_f32 v[46:47], v[26:27], v[156:157], v[46:47] op_sel_hi:[0,1,1]
	v_pk_fma_f32 v[34:35], v[22:23], v[156:157], v[34:35] op_sel_hi:[0,1,1]
	v_pk_fma_f32 v[46:47], v[26:27], v[158:159], v[46:47] op_sel:[1,0,0] op_sel_hi:[1,1,1]
	v_pk_fma_f32 v[34:35], v[22:23], v[158:159], v[34:35] op_sel:[1,0,0] op_sel_hi:[1,1,1]
	v_pk_mul_f32 v[20:21], v[20:21], v[168:169]
	v_add_f32_dpp v28, v46, v34 row_half_mirror row_mask:0xf bank_mask:0xf
	v_add_f32_dpp v32, v47, v35 row_half_mirror row_mask:0xf bank_mask:0xf
	v_pk_mul_f32 v[22:23], v[22:23], v[170:171]
	v_add_f32_dpp v28, v28, v28 row_ror:8 row_mask:0xf bank_mask:0xf
	v_add_f32_dpp v32, v32, v32 row_ror:8 row_mask:0xf bank_mask:0xf
	v_pk_mul_f32 v[24:25], v[24:25], v[168:169]
	v_add_f32_dpp v28, v28, v28 quad_perm:[1,0,3,2] row_mask:0xf bank_mask:0xf
	v_add_f32_dpp v32, v32, v32 quad_perm:[1,0,3,2] row_mask:0xf bank_mask:0xf
	v_pk_mul_f32 v[26:27], v[26:27], v[170:171]
	v_add_f32_dpp v28, v28, v28 quad_perm:[2,3,0,1] row_mask:0xf bank_mask:0xf
	v_add_f32_dpp v32, v32, v32 quad_perm:[2,3,0,1] row_mask:0xf bank_mask:0xf
	v_pk_fma_f32 v[20:21], v[180:181], v[8:9], v[20:21] op_sel_hi:[1,0,1]
	v_mov_b32_dpp v30, v28 row_half_mirror row_mask:0xf bank_mask:0xf
	v_pk_fma_f32 v[22:23], v[182:183], v[8:9], v[22:23] op_sel_hi:[1,0,1]
	v_pk_fma_f32 v[24:25], v[180:181], v[10:11], v[24:25] op_sel_hi:[1,0,1]
	v_pk_fma_f32 v[26:27], v[182:183], v[10:11], v[26:27] op_sel_hi:[1,0,1]
	v_pk_fma_f32 v[20:21], v[88:89], v[28:29], v[20:21] op_sel_hi:[1,0,1] neg_lo:[0,1,0] neg_hi:[0,1,0]
	v_pk_fma_f32 v[22:23], v[90:91], v[28:29], v[22:23] op_sel_hi:[1,0,1] neg_lo:[0,1,0] neg_hi:[0,1,0]
	v_pk_fma_f32 v[24:25], v[88:89], v[30:31], v[24:25] op_sel_hi:[1,0,1] neg_lo:[0,1,0] neg_hi:[0,1,0]
	v_pk_fma_f32 v[26:27], v[90:91], v[30:31], v[26:27] op_sel_hi:[1,0,1] neg_lo:[0,1,0] neg_hi:[0,1,0]
	v_add_f32_e32 v39, v32, v9
	ds_write_b32 v102, v39 offset:512
	ds_read_b128 v[144:147], v195 offset:1792
	ds_read_b128 v[156:159], v195 offset:9984
	ds_read_b128 v[168:171], v195 offset:26368
	ds_read_b128 v[180:183], v195 offset:18176
	ds_read_b128 v[88:91], v195 offset:34560
	ds_read_b64 v[8:9], v196 offset:3584
	ds_read_b64 v[10:11], v36 offset:3584
	s_waitcnt lgkmcnt(15)
	v_pk_mul_f32 v[46:47], v[24:25], v[148:149] op_sel_hi:[0,1]
	v_pk_mul_f32 v[34:35], v[20:21], v[148:149] op_sel_hi:[0,1]
	v_pk_fma_f32 v[46:47], v[24:25], v[150:151], v[46:47] op_sel:[1,0,0] op_sel_hi:[1,1,1]
	v_pk_fma_f32 v[34:35], v[20:21], v[150:151], v[34:35] op_sel:[1,0,0] op_sel_hi:[1,1,1]
	v_pk_fma_f32 v[46:47], v[26:27], v[160:161], v[46:47] op_sel_hi:[0,1,1]
	v_pk_fma_f32 v[34:35], v[22:23], v[160:161], v[34:35] op_sel_hi:[0,1,1]
	v_pk_fma_f32 v[46:47], v[26:27], v[162:163], v[46:47] op_sel:[1,0,0] op_sel_hi:[1,1,1]
	v_pk_fma_f32 v[34:35], v[22:23], v[162:163], v[34:35] op_sel:[1,0,0] op_sel_hi:[1,1,1]
	v_pk_mul_f32 v[20:21], v[20:21], v[172:173]
	v_add_f32_dpp v28, v46, v34 row_half_mirror row_mask:0xf bank_mask:0xf
	v_add_f32_dpp v32, v47, v35 row_half_mirror row_mask:0xf bank_mask:0xf
	v_pk_mul_f32 v[22:23], v[22:23], v[174:175]
	v_add_f32_dpp v28, v28, v28 row_ror:8 row_mask:0xf bank_mask:0xf
	v_add_f32_dpp v32, v32, v32 row_ror:8 row_mask:0xf bank_mask:0xf
	v_pk_mul_f32 v[24:25], v[24:25], v[172:173]
	v_add_f32_dpp v28, v28, v28 quad_perm:[1,0,3,2] row_mask:0xf bank_mask:0xf
	v_add_f32_dpp v32, v32, v32 quad_perm:[1,0,3,2] row_mask:0xf bank_mask:0xf
	v_pk_mul_f32 v[26:27], v[26:27], v[174:175]
	v_add_f32_dpp v28, v28, v28 quad_perm:[2,3,0,1] row_mask:0xf bank_mask:0xf
	v_add_f32_dpp v32, v32, v32 quad_perm:[2,3,0,1] row_mask:0xf bank_mask:0xf
	v_pk_fma_f32 v[20:21], v[184:185], v[12:13], v[20:21] op_sel_hi:[1,0,1]
	v_mov_b32_dpp v30, v28 row_half_mirror row_mask:0xf bank_mask:0xf
	v_pk_fma_f32 v[22:23], v[186:187], v[12:13], v[22:23] op_sel_hi:[1,0,1]
	v_pk_fma_f32 v[24:25], v[184:185], v[14:15], v[24:25] op_sel_hi:[1,0,1]
	v_pk_fma_f32 v[26:27], v[186:187], v[14:15], v[26:27] op_sel_hi:[1,0,1]
	v_pk_fma_f32 v[20:21], v[92:93], v[28:29], v[20:21] op_sel_hi:[1,0,1] neg_lo:[0,1,0] neg_hi:[0,1,0]
	v_pk_fma_f32 v[22:23], v[94:95], v[28:29], v[22:23] op_sel_hi:[1,0,1] neg_lo:[0,1,0] neg_hi:[0,1,0]
	v_pk_fma_f32 v[24:25], v[92:93], v[30:31], v[24:25] op_sel_hi:[1,0,1] neg_lo:[0,1,0] neg_hi:[0,1,0]
	v_pk_fma_f32 v[26:27], v[94:95], v[30:31], v[26:27] op_sel_hi:[1,0,1] neg_lo:[0,1,0] neg_hi:[0,1,0]
	v_add_f32_e32 v39, v32, v13
	ds_write_b32 v102, v39 offset:640
	ds_read_b128 v[148:151], v195 offset:2048
	ds_read_b128 v[160:163], v195 offset:10240
	ds_read_b128 v[172:175], v195 offset:26624
	ds_read_b128 v[184:187], v195 offset:18432
	ds_read_b128 v[92:95], v195 offset:34816
	ds_read_b64 v[12:13], v196 offset:4096
	ds_read_b64 v[14:15], v36 offset:4096
	s_waitcnt lgkmcnt(15)
	v_pk_mul_f32 v[46:47], v[24:25], v[140:141] op_sel_hi:[0,1]
	v_pk_mul_f32 v[34:35], v[20:21], v[140:141] op_sel_hi:[0,1]
	v_pk_fma_f32 v[46:47], v[24:25], v[142:143], v[46:47] op_sel:[1,0,0] op_sel_hi:[1,1,1]
	v_pk_fma_f32 v[34:35], v[20:21], v[142:143], v[34:35] op_sel:[1,0,0] op_sel_hi:[1,1,1]
	v_pk_fma_f32 v[46:47], v[26:27], v[152:153], v[46:47] op_sel_hi:[0,1,1]
	v_pk_fma_f32 v[34:35], v[22:23], v[152:153], v[34:35] op_sel_hi:[0,1,1]
	v_pk_fma_f32 v[46:47], v[26:27], v[154:155], v[46:47] op_sel:[1,0,0] op_sel_hi:[1,1,1]
	v_pk_fma_f32 v[34:35], v[22:23], v[154:155], v[34:35] op_sel:[1,0,0] op_sel_hi:[1,1,1]
	v_pk_mul_f32 v[20:21], v[20:21], v[164:165]
	v_add_f32_dpp v28, v46, v34 row_half_mirror row_mask:0xf bank_mask:0xf
	v_add_f32_dpp v32, v47, v35 row_half_mirror row_mask:0xf bank_mask:0xf
	v_pk_mul_f32 v[22:23], v[22:23], v[166:167]
	v_add_f32_dpp v28, v28, v28 row_ror:8 row_mask:0xf bank_mask:0xf
	v_add_f32_dpp v32, v32, v32 row_ror:8 row_mask:0xf bank_mask:0xf
	v_pk_mul_f32 v[24:25], v[24:25], v[164:165]
	v_add_f32_dpp v28, v28, v28 quad_perm:[1,0,3,2] row_mask:0xf bank_mask:0xf
	v_add_f32_dpp v32, v32, v32 quad_perm:[1,0,3,2] row_mask:0xf bank_mask:0xf
	v_pk_mul_f32 v[26:27], v[26:27], v[166:167]
	v_add_f32_dpp v28, v28, v28 quad_perm:[2,3,0,1] row_mask:0xf bank_mask:0xf
	v_add_f32_dpp v32, v32, v32 quad_perm:[2,3,0,1] row_mask:0xf bank_mask:0xf
	v_pk_fma_f32 v[20:21], v[176:177], v[4:5], v[20:21] op_sel_hi:[1,0,1]
	v_mov_b32_dpp v30, v28 row_half_mirror row_mask:0xf bank_mask:0xf
	v_pk_fma_f32 v[22:23], v[178:179], v[4:5], v[22:23] op_sel_hi:[1,0,1]
	v_pk_fma_f32 v[24:25], v[176:177], v[6:7], v[24:25] op_sel_hi:[1,0,1]
	v_pk_fma_f32 v[26:27], v[178:179], v[6:7], v[26:27] op_sel_hi:[1,0,1]
	v_pk_fma_f32 v[20:21], v[84:85], v[28:29], v[20:21] op_sel_hi:[1,0,1] neg_lo:[0,1,0] neg_hi:[0,1,0]
	v_pk_fma_f32 v[22:23], v[86:87], v[28:29], v[22:23] op_sel_hi:[1,0,1] neg_lo:[0,1,0] neg_hi:[0,1,0]
	v_pk_fma_f32 v[24:25], v[84:85], v[30:31], v[24:25] op_sel_hi:[1,0,1] neg_lo:[0,1,0] neg_hi:[0,1,0]
	v_pk_fma_f32 v[26:27], v[86:87], v[30:31], v[26:27] op_sel_hi:[1,0,1] neg_lo:[0,1,0] neg_hi:[0,1,0]
	v_add_f32_e32 v39, v32, v5
	ds_write_b32 v102, v39 offset:768
	ds_read_b128 v[140:143], v195 offset:2304
	ds_read_b128 v[152:155], v195 offset:10496
	ds_read_b128 v[164:167], v195 offset:26880
	ds_read_b128 v[176:179], v195 offset:18688
	ds_read_b128 v[84:87], v195 offset:35072
	ds_read_b64 v[4:5], v196 offset:4608
	ds_read_b64 v[6:7], v36 offset:4608
	s_waitcnt lgkmcnt(15)
	v_pk_mul_f32 v[46:47], v[24:25], v[144:145] op_sel_hi:[0,1]
	v_pk_mul_f32 v[34:35], v[20:21], v[144:145] op_sel_hi:[0,1]
	v_pk_fma_f32 v[46:47], v[24:25], v[146:147], v[46:47] op_sel:[1,0,0] op_sel_hi:[1,1,1]
	v_pk_fma_f32 v[34:35], v[20:21], v[146:147], v[34:35] op_sel:[1,0,0] op_sel_hi:[1,1,1]
	v_pk_fma_f32 v[46:47], v[26:27], v[156:157], v[46:47] op_sel_hi:[0,1,1]
	v_pk_fma_f32 v[34:35], v[22:23], v[156:157], v[34:35] op_sel_hi:[0,1,1]
	v_pk_fma_f32 v[46:47], v[26:27], v[158:159], v[46:47] op_sel:[1,0,0] op_sel_hi:[1,1,1]
	v_pk_fma_f32 v[34:35], v[22:23], v[158:159], v[34:35] op_sel:[1,0,0] op_sel_hi:[1,1,1]
	v_pk_mul_f32 v[20:21], v[20:21], v[168:169]
	v_add_f32_dpp v28, v46, v34 row_half_mirror row_mask:0xf bank_mask:0xf
	v_add_f32_dpp v32, v47, v35 row_half_mirror row_mask:0xf bank_mask:0xf
	v_pk_mul_f32 v[22:23], v[22:23], v[170:171]
	v_add_f32_dpp v28, v28, v28 row_ror:8 row_mask:0xf bank_mask:0xf
	v_add_f32_dpp v32, v32, v32 row_ror:8 row_mask:0xf bank_mask:0xf
	v_pk_mul_f32 v[24:25], v[24:25], v[168:169]
	v_add_f32_dpp v28, v28, v28 quad_perm:[1,0,3,2] row_mask:0xf bank_mask:0xf
	v_add_f32_dpp v32, v32, v32 quad_perm:[1,0,3,2] row_mask:0xf bank_mask:0xf
	v_pk_mul_f32 v[26:27], v[26:27], v[170:171]
	v_add_f32_dpp v28, v28, v28 quad_perm:[2,3,0,1] row_mask:0xf bank_mask:0xf
	v_add_f32_dpp v32, v32, v32 quad_perm:[2,3,0,1] row_mask:0xf bank_mask:0xf
	v_pk_fma_f32 v[20:21], v[180:181], v[8:9], v[20:21] op_sel_hi:[1,0,1]
	v_mov_b32_dpp v30, v28 row_half_mirror row_mask:0xf bank_mask:0xf
	v_pk_fma_f32 v[22:23], v[182:183], v[8:9], v[22:23] op_sel_hi:[1,0,1]
	v_pk_fma_f32 v[24:25], v[180:181], v[10:11], v[24:25] op_sel_hi:[1,0,1]
	v_pk_fma_f32 v[26:27], v[182:183], v[10:11], v[26:27] op_sel_hi:[1,0,1]
	v_pk_fma_f32 v[20:21], v[88:89], v[28:29], v[20:21] op_sel_hi:[1,0,1] neg_lo:[0,1,0] neg_hi:[0,1,0]
	v_pk_fma_f32 v[22:23], v[90:91], v[28:29], v[22:23] op_sel_hi:[1,0,1] neg_lo:[0,1,0] neg_hi:[0,1,0]
	v_pk_fma_f32 v[24:25], v[88:89], v[30:31], v[24:25] op_sel_hi:[1,0,1] neg_lo:[0,1,0] neg_hi:[0,1,0]
	v_pk_fma_f32 v[26:27], v[90:91], v[30:31], v[26:27] op_sel_hi:[1,0,1] neg_lo:[0,1,0] neg_hi:[0,1,0]
	v_add_f32_e32 v39, v32, v9
	ds_write_b32 v102, v39 offset:896
	ds_read_b128 v[144:147], v195 offset:2560
	ds_read_b128 v[156:159], v195 offset:10752
	ds_read_b128 v[168:171], v195 offset:27136
	ds_read_b128 v[180:183], v195 offset:18944
	ds_read_b128 v[88:91], v195 offset:35328
	ds_read_b64 v[8:9], v196 offset:5120
	ds_read_b64 v[10:11], v36 offset:5120
	s_waitcnt lgkmcnt(15)
	v_pk_mul_f32 v[46:47], v[24:25], v[148:149] op_sel_hi:[0,1]
	v_pk_mul_f32 v[34:35], v[20:21], v[148:149] op_sel_hi:[0,1]
	v_pk_fma_f32 v[46:47], v[24:25], v[150:151], v[46:47] op_sel:[1,0,0] op_sel_hi:[1,1,1]
	v_pk_fma_f32 v[34:35], v[20:21], v[150:151], v[34:35] op_sel:[1,0,0] op_sel_hi:[1,1,1]
	v_pk_fma_f32 v[46:47], v[26:27], v[160:161], v[46:47] op_sel_hi:[0,1,1]
	v_pk_fma_f32 v[34:35], v[22:23], v[160:161], v[34:35] op_sel_hi:[0,1,1]
	v_pk_fma_f32 v[46:47], v[26:27], v[162:163], v[46:47] op_sel:[1,0,0] op_sel_hi:[1,1,1]
	v_pk_fma_f32 v[34:35], v[22:23], v[162:163], v[34:35] op_sel:[1,0,0] op_sel_hi:[1,1,1]
	v_pk_mul_f32 v[20:21], v[20:21], v[172:173]
	v_add_f32_dpp v28, v46, v34 row_half_mirror row_mask:0xf bank_mask:0xf
	v_add_f32_dpp v32, v47, v35 row_half_mirror row_mask:0xf bank_mask:0xf
	v_pk_mul_f32 v[22:23], v[22:23], v[174:175]
	v_add_f32_dpp v28, v28, v28 row_ror:8 row_mask:0xf bank_mask:0xf
	v_add_f32_dpp v32, v32, v32 row_ror:8 row_mask:0xf bank_mask:0xf
	v_pk_mul_f32 v[24:25], v[24:25], v[172:173]
	v_add_f32_dpp v28, v28, v28 quad_perm:[1,0,3,2] row_mask:0xf bank_mask:0xf
	v_add_f32_dpp v32, v32, v32 quad_perm:[1,0,3,2] row_mask:0xf bank_mask:0xf
	v_pk_mul_f32 v[26:27], v[26:27], v[174:175]
	v_add_f32_dpp v28, v28, v28 quad_perm:[2,3,0,1] row_mask:0xf bank_mask:0xf
	v_add_f32_dpp v32, v32, v32 quad_perm:[2,3,0,1] row_mask:0xf bank_mask:0xf
	v_pk_fma_f32 v[20:21], v[184:185], v[12:13], v[20:21] op_sel_hi:[1,0,1]
	v_mov_b32_dpp v30, v28 row_half_mirror row_mask:0xf bank_mask:0xf
	v_pk_fma_f32 v[22:23], v[186:187], v[12:13], v[22:23] op_sel_hi:[1,0,1]
	v_pk_fma_f32 v[24:25], v[184:185], v[14:15], v[24:25] op_sel_hi:[1,0,1]
	v_pk_fma_f32 v[26:27], v[186:187], v[14:15], v[26:27] op_sel_hi:[1,0,1]
	v_pk_fma_f32 v[20:21], v[92:93], v[28:29], v[20:21] op_sel_hi:[1,0,1] neg_lo:[0,1,0] neg_hi:[0,1,0]
	v_pk_fma_f32 v[22:23], v[94:95], v[28:29], v[22:23] op_sel_hi:[1,0,1] neg_lo:[0,1,0] neg_hi:[0,1,0]
	v_pk_fma_f32 v[24:25], v[92:93], v[30:31], v[24:25] op_sel_hi:[1,0,1] neg_lo:[0,1,0] neg_hi:[0,1,0]
	v_pk_fma_f32 v[26:27], v[94:95], v[30:31], v[26:27] op_sel_hi:[1,0,1] neg_lo:[0,1,0] neg_hi:[0,1,0]
	v_add_f32_e32 v39, v32, v13
	ds_write_b32 v102, v39 offset:1024
	ds_read_b128 v[148:151], v195 offset:2816
	ds_read_b128 v[160:163], v195 offset:11008
	ds_read_b128 v[172:175], v195 offset:27392
	ds_read_b128 v[184:187], v195 offset:19200
	ds_read_b128 v[92:95], v195 offset:35584
	ds_read_b64 v[12:13], v196 offset:5632
	ds_read_b64 v[14:15], v36 offset:5632
	s_waitcnt lgkmcnt(15)
	v_pk_mul_f32 v[46:47], v[24:25], v[140:141] op_sel_hi:[0,1]
	v_pk_mul_f32 v[34:35], v[20:21], v[140:141] op_sel_hi:[0,1]
	v_pk_fma_f32 v[46:47], v[24:25], v[142:143], v[46:47] op_sel:[1,0,0] op_sel_hi:[1,1,1]
	v_pk_fma_f32 v[34:35], v[20:21], v[142:143], v[34:35] op_sel:[1,0,0] op_sel_hi:[1,1,1]
	v_pk_fma_f32 v[46:47], v[26:27], v[152:153], v[46:47] op_sel_hi:[0,1,1]
	v_pk_fma_f32 v[34:35], v[22:23], v[152:153], v[34:35] op_sel_hi:[0,1,1]
	v_pk_fma_f32 v[46:47], v[26:27], v[154:155], v[46:47] op_sel:[1,0,0] op_sel_hi:[1,1,1]
	v_pk_fma_f32 v[34:35], v[22:23], v[154:155], v[34:35] op_sel:[1,0,0] op_sel_hi:[1,1,1]
	v_pk_mul_f32 v[20:21], v[20:21], v[164:165]
	v_add_f32_dpp v28, v46, v34 row_half_mirror row_mask:0xf bank_mask:0xf
	v_add_f32_dpp v32, v47, v35 row_half_mirror row_mask:0xf bank_mask:0xf
	v_pk_mul_f32 v[22:23], v[22:23], v[166:167]
	v_add_f32_dpp v28, v28, v28 row_ror:8 row_mask:0xf bank_mask:0xf
	v_add_f32_dpp v32, v32, v32 row_ror:8 row_mask:0xf bank_mask:0xf
	v_pk_mul_f32 v[24:25], v[24:25], v[164:165]
	v_add_f32_dpp v28, v28, v28 quad_perm:[1,0,3,2] row_mask:0xf bank_mask:0xf
	v_add_f32_dpp v32, v32, v32 quad_perm:[1,0,3,2] row_mask:0xf bank_mask:0xf
	v_pk_mul_f32 v[26:27], v[26:27], v[166:167]
	v_add_f32_dpp v28, v28, v28 quad_perm:[2,3,0,1] row_mask:0xf bank_mask:0xf
	v_add_f32_dpp v32, v32, v32 quad_perm:[2,3,0,1] row_mask:0xf bank_mask:0xf
	v_pk_fma_f32 v[20:21], v[176:177], v[4:5], v[20:21] op_sel_hi:[1,0,1]
	v_mov_b32_dpp v30, v28 row_half_mirror row_mask:0xf bank_mask:0xf
	v_pk_fma_f32 v[22:23], v[178:179], v[4:5], v[22:23] op_sel_hi:[1,0,1]
	v_pk_fma_f32 v[24:25], v[176:177], v[6:7], v[24:25] op_sel_hi:[1,0,1]
	v_pk_fma_f32 v[26:27], v[178:179], v[6:7], v[26:27] op_sel_hi:[1,0,1]
	v_pk_fma_f32 v[20:21], v[84:85], v[28:29], v[20:21] op_sel_hi:[1,0,1] neg_lo:[0,1,0] neg_hi:[0,1,0]
	v_pk_fma_f32 v[22:23], v[86:87], v[28:29], v[22:23] op_sel_hi:[1,0,1] neg_lo:[0,1,0] neg_hi:[0,1,0]
	v_pk_fma_f32 v[24:25], v[84:85], v[30:31], v[24:25] op_sel_hi:[1,0,1] neg_lo:[0,1,0] neg_hi:[0,1,0]
	v_pk_fma_f32 v[26:27], v[86:87], v[30:31], v[26:27] op_sel_hi:[1,0,1] neg_lo:[0,1,0] neg_hi:[0,1,0]
	v_add_f32_e32 v39, v32, v5
	ds_write_b32 v102, v39 offset:1152
	ds_read_b128 v[140:143], v195 offset:3072
	ds_read_b128 v[152:155], v195 offset:11264
	ds_read_b128 v[164:167], v195 offset:27648
	ds_read_b128 v[176:179], v195 offset:19456
	ds_read_b128 v[84:87], v195 offset:35840
	ds_read_b64 v[4:5], v196 offset:6144
	ds_read_b64 v[6:7], v36 offset:6144
	s_waitcnt lgkmcnt(15)
	v_pk_mul_f32 v[46:47], v[24:25], v[144:145] op_sel_hi:[0,1]
	v_pk_mul_f32 v[34:35], v[20:21], v[144:145] op_sel_hi:[0,1]
	v_pk_fma_f32 v[46:47], v[24:25], v[146:147], v[46:47] op_sel:[1,0,0] op_sel_hi:[1,1,1]
	v_pk_fma_f32 v[34:35], v[20:21], v[146:147], v[34:35] op_sel:[1,0,0] op_sel_hi:[1,1,1]
	v_pk_fma_f32 v[46:47], v[26:27], v[156:157], v[46:47] op_sel_hi:[0,1,1]
	v_pk_fma_f32 v[34:35], v[22:23], v[156:157], v[34:35] op_sel_hi:[0,1,1]
	v_pk_fma_f32 v[46:47], v[26:27], v[158:159], v[46:47] op_sel:[1,0,0] op_sel_hi:[1,1,1]
	v_pk_fma_f32 v[34:35], v[22:23], v[158:159], v[34:35] op_sel:[1,0,0] op_sel_hi:[1,1,1]
	v_pk_mul_f32 v[20:21], v[20:21], v[168:169]
	v_add_f32_dpp v28, v46, v34 row_half_mirror row_mask:0xf bank_mask:0xf
	v_add_f32_dpp v32, v47, v35 row_half_mirror row_mask:0xf bank_mask:0xf
	v_pk_mul_f32 v[22:23], v[22:23], v[170:171]
	v_add_f32_dpp v28, v28, v28 row_ror:8 row_mask:0xf bank_mask:0xf
	v_add_f32_dpp v32, v32, v32 row_ror:8 row_mask:0xf bank_mask:0xf
	v_pk_mul_f32 v[24:25], v[24:25], v[168:169]
	v_add_f32_dpp v28, v28, v28 quad_perm:[1,0,3,2] row_mask:0xf bank_mask:0xf
	v_add_f32_dpp v32, v32, v32 quad_perm:[1,0,3,2] row_mask:0xf bank_mask:0xf
	v_pk_mul_f32 v[26:27], v[26:27], v[170:171]
	v_add_f32_dpp v28, v28, v28 quad_perm:[2,3,0,1] row_mask:0xf bank_mask:0xf
	v_add_f32_dpp v32, v32, v32 quad_perm:[2,3,0,1] row_mask:0xf bank_mask:0xf
	v_pk_fma_f32 v[20:21], v[180:181], v[8:9], v[20:21] op_sel_hi:[1,0,1]
	v_mov_b32_dpp v30, v28 row_half_mirror row_mask:0xf bank_mask:0xf
	v_pk_fma_f32 v[22:23], v[182:183], v[8:9], v[22:23] op_sel_hi:[1,0,1]
	v_pk_fma_f32 v[24:25], v[180:181], v[10:11], v[24:25] op_sel_hi:[1,0,1]
	v_pk_fma_f32 v[26:27], v[182:183], v[10:11], v[26:27] op_sel_hi:[1,0,1]
	v_pk_fma_f32 v[20:21], v[88:89], v[28:29], v[20:21] op_sel_hi:[1,0,1] neg_lo:[0,1,0] neg_hi:[0,1,0]
	v_pk_fma_f32 v[22:23], v[90:91], v[28:29], v[22:23] op_sel_hi:[1,0,1] neg_lo:[0,1,0] neg_hi:[0,1,0]
	v_pk_fma_f32 v[24:25], v[88:89], v[30:31], v[24:25] op_sel_hi:[1,0,1] neg_lo:[0,1,0] neg_hi:[0,1,0]
	v_pk_fma_f32 v[26:27], v[90:91], v[30:31], v[26:27] op_sel_hi:[1,0,1] neg_lo:[0,1,0] neg_hi:[0,1,0]
	v_add_f32_e32 v39, v32, v9
	ds_write_b32 v102, v39 offset:1280
	ds_read_b128 v[144:147], v195 offset:3328
	ds_read_b128 v[156:159], v195 offset:11520
	ds_read_b128 v[168:171], v195 offset:27904
	ds_read_b128 v[180:183], v195 offset:19712
	ds_read_b128 v[88:91], v195 offset:36096
	ds_read_b64 v[8:9], v196 offset:6656
	ds_read_b64 v[10:11], v36 offset:6656
	s_waitcnt lgkmcnt(15)
	v_pk_mul_f32 v[46:47], v[24:25], v[148:149] op_sel_hi:[0,1]
	v_pk_mul_f32 v[34:35], v[20:21], v[148:149] op_sel_hi:[0,1]
	v_pk_fma_f32 v[46:47], v[24:25], v[150:151], v[46:47] op_sel:[1,0,0] op_sel_hi:[1,1,1]
	v_pk_fma_f32 v[34:35], v[20:21], v[150:151], v[34:35] op_sel:[1,0,0] op_sel_hi:[1,1,1]
	v_pk_fma_f32 v[46:47], v[26:27], v[160:161], v[46:47] op_sel_hi:[0,1,1]
	v_pk_fma_f32 v[34:35], v[22:23], v[160:161], v[34:35] op_sel_hi:[0,1,1]
	v_pk_fma_f32 v[46:47], v[26:27], v[162:163], v[46:47] op_sel:[1,0,0] op_sel_hi:[1,1,1]
	v_pk_fma_f32 v[34:35], v[22:23], v[162:163], v[34:35] op_sel:[1,0,0] op_sel_hi:[1,1,1]
	v_pk_mul_f32 v[20:21], v[20:21], v[172:173]
	v_add_f32_dpp v28, v46, v34 row_half_mirror row_mask:0xf bank_mask:0xf
	v_add_f32_dpp v32, v47, v35 row_half_mirror row_mask:0xf bank_mask:0xf
	v_pk_mul_f32 v[22:23], v[22:23], v[174:175]
	v_add_f32_dpp v28, v28, v28 row_ror:8 row_mask:0xf bank_mask:0xf
	v_add_f32_dpp v32, v32, v32 row_ror:8 row_mask:0xf bank_mask:0xf
	v_pk_mul_f32 v[24:25], v[24:25], v[172:173]
	v_add_f32_dpp v28, v28, v28 quad_perm:[1,0,3,2] row_mask:0xf bank_mask:0xf
	v_add_f32_dpp v32, v32, v32 quad_perm:[1,0,3,2] row_mask:0xf bank_mask:0xf
	v_pk_mul_f32 v[26:27], v[26:27], v[174:175]
	v_add_f32_dpp v28, v28, v28 quad_perm:[2,3,0,1] row_mask:0xf bank_mask:0xf
	v_add_f32_dpp v32, v32, v32 quad_perm:[2,3,0,1] row_mask:0xf bank_mask:0xf
	v_pk_fma_f32 v[20:21], v[184:185], v[12:13], v[20:21] op_sel_hi:[1,0,1]
	v_mov_b32_dpp v30, v28 row_half_mirror row_mask:0xf bank_mask:0xf
	v_pk_fma_f32 v[22:23], v[186:187], v[12:13], v[22:23] op_sel_hi:[1,0,1]
	v_pk_fma_f32 v[24:25], v[184:185], v[14:15], v[24:25] op_sel_hi:[1,0,1]
	v_pk_fma_f32 v[26:27], v[186:187], v[14:15], v[26:27] op_sel_hi:[1,0,1]
	v_pk_fma_f32 v[20:21], v[92:93], v[28:29], v[20:21] op_sel_hi:[1,0,1] neg_lo:[0,1,0] neg_hi:[0,1,0]
	v_pk_fma_f32 v[22:23], v[94:95], v[28:29], v[22:23] op_sel_hi:[1,0,1] neg_lo:[0,1,0] neg_hi:[0,1,0]
	v_pk_fma_f32 v[24:25], v[92:93], v[30:31], v[24:25] op_sel_hi:[1,0,1] neg_lo:[0,1,0] neg_hi:[0,1,0]
	v_pk_fma_f32 v[26:27], v[94:95], v[30:31], v[26:27] op_sel_hi:[1,0,1] neg_lo:[0,1,0] neg_hi:[0,1,0]
	v_add_f32_e32 v39, v32, v13
	ds_write_b32 v102, v39 offset:1408
	ds_read_b128 v[148:151], v195 offset:3584
	ds_read_b128 v[160:163], v195 offset:11776
	ds_read_b128 v[172:175], v195 offset:28160
	ds_read_b128 v[184:187], v195 offset:19968
	ds_read_b128 v[92:95], v195 offset:36352
	ds_read_b64 v[12:13], v196 offset:7168
	ds_read_b64 v[14:15], v36 offset:7168
	s_waitcnt lgkmcnt(15)
	v_pk_mul_f32 v[46:47], v[24:25], v[140:141] op_sel_hi:[0,1]
	v_pk_mul_f32 v[34:35], v[20:21], v[140:141] op_sel_hi:[0,1]
	v_pk_fma_f32 v[46:47], v[24:25], v[142:143], v[46:47] op_sel:[1,0,0] op_sel_hi:[1,1,1]
	v_pk_fma_f32 v[34:35], v[20:21], v[142:143], v[34:35] op_sel:[1,0,0] op_sel_hi:[1,1,1]
	v_pk_fma_f32 v[46:47], v[26:27], v[152:153], v[46:47] op_sel_hi:[0,1,1]
	v_pk_fma_f32 v[34:35], v[22:23], v[152:153], v[34:35] op_sel_hi:[0,1,1]
	v_pk_fma_f32 v[46:47], v[26:27], v[154:155], v[46:47] op_sel:[1,0,0] op_sel_hi:[1,1,1]
	v_pk_fma_f32 v[34:35], v[22:23], v[154:155], v[34:35] op_sel:[1,0,0] op_sel_hi:[1,1,1]
	v_pk_mul_f32 v[20:21], v[20:21], v[164:165]
	v_add_f32_dpp v28, v46, v34 row_half_mirror row_mask:0xf bank_mask:0xf
	v_add_f32_dpp v32, v47, v35 row_half_mirror row_mask:0xf bank_mask:0xf
	v_pk_mul_f32 v[22:23], v[22:23], v[166:167]
	v_add_f32_dpp v28, v28, v28 row_ror:8 row_mask:0xf bank_mask:0xf
	v_add_f32_dpp v32, v32, v32 row_ror:8 row_mask:0xf bank_mask:0xf
	v_pk_mul_f32 v[24:25], v[24:25], v[164:165]
	v_add_f32_dpp v28, v28, v28 quad_perm:[1,0,3,2] row_mask:0xf bank_mask:0xf
	v_add_f32_dpp v32, v32, v32 quad_perm:[1,0,3,2] row_mask:0xf bank_mask:0xf
	v_pk_mul_f32 v[26:27], v[26:27], v[166:167]
	v_add_f32_dpp v28, v28, v28 quad_perm:[2,3,0,1] row_mask:0xf bank_mask:0xf
	v_add_f32_dpp v32, v32, v32 quad_perm:[2,3,0,1] row_mask:0xf bank_mask:0xf
	v_pk_fma_f32 v[20:21], v[176:177], v[4:5], v[20:21] op_sel_hi:[1,0,1]
	v_mov_b32_dpp v30, v28 row_half_mirror row_mask:0xf bank_mask:0xf
	v_pk_fma_f32 v[22:23], v[178:179], v[4:5], v[22:23] op_sel_hi:[1,0,1]
	v_pk_fma_f32 v[24:25], v[176:177], v[6:7], v[24:25] op_sel_hi:[1,0,1]
	v_pk_fma_f32 v[26:27], v[178:179], v[6:7], v[26:27] op_sel_hi:[1,0,1]
	v_pk_fma_f32 v[20:21], v[84:85], v[28:29], v[20:21] op_sel_hi:[1,0,1] neg_lo:[0,1,0] neg_hi:[0,1,0]
	v_pk_fma_f32 v[22:23], v[86:87], v[28:29], v[22:23] op_sel_hi:[1,0,1] neg_lo:[0,1,0] neg_hi:[0,1,0]
	v_pk_fma_f32 v[24:25], v[84:85], v[30:31], v[24:25] op_sel_hi:[1,0,1] neg_lo:[0,1,0] neg_hi:[0,1,0]
	v_pk_fma_f32 v[26:27], v[86:87], v[30:31], v[26:27] op_sel_hi:[1,0,1] neg_lo:[0,1,0] neg_hi:[0,1,0]
	v_add_f32_e32 v39, v32, v5
	ds_write_b32 v102, v39 offset:1536
	ds_read_b128 v[140:143], v195 offset:3840
	ds_read_b128 v[152:155], v195 offset:12032
	ds_read_b128 v[164:167], v195 offset:28416
	ds_read_b128 v[176:179], v195 offset:20224
	ds_read_b128 v[84:87], v195 offset:36608
	ds_read_b64 v[4:5], v196 offset:7680
	ds_read_b64 v[6:7], v36 offset:7680
	s_waitcnt lgkmcnt(15)
	v_pk_mul_f32 v[46:47], v[24:25], v[144:145] op_sel_hi:[0,1]
	v_pk_mul_f32 v[34:35], v[20:21], v[144:145] op_sel_hi:[0,1]
	v_pk_fma_f32 v[46:47], v[24:25], v[146:147], v[46:47] op_sel:[1,0,0] op_sel_hi:[1,1,1]
	v_pk_fma_f32 v[34:35], v[20:21], v[146:147], v[34:35] op_sel:[1,0,0] op_sel_hi:[1,1,1]
	v_pk_fma_f32 v[46:47], v[26:27], v[156:157], v[46:47] op_sel_hi:[0,1,1]
	v_pk_fma_f32 v[34:35], v[22:23], v[156:157], v[34:35] op_sel_hi:[0,1,1]
	v_pk_fma_f32 v[46:47], v[26:27], v[158:159], v[46:47] op_sel:[1,0,0] op_sel_hi:[1,1,1]
	v_pk_fma_f32 v[34:35], v[22:23], v[158:159], v[34:35] op_sel:[1,0,0] op_sel_hi:[1,1,1]
	v_pk_mul_f32 v[20:21], v[20:21], v[168:169]
	v_add_f32_dpp v28, v46, v34 row_half_mirror row_mask:0xf bank_mask:0xf
	v_add_f32_dpp v32, v47, v35 row_half_mirror row_mask:0xf bank_mask:0xf
	v_pk_mul_f32 v[22:23], v[22:23], v[170:171]
	v_add_f32_dpp v28, v28, v28 row_ror:8 row_mask:0xf bank_mask:0xf
	v_add_f32_dpp v32, v32, v32 row_ror:8 row_mask:0xf bank_mask:0xf
	v_pk_mul_f32 v[24:25], v[24:25], v[168:169]
	v_add_f32_dpp v28, v28, v28 quad_perm:[1,0,3,2] row_mask:0xf bank_mask:0xf
	v_add_f32_dpp v32, v32, v32 quad_perm:[1,0,3,2] row_mask:0xf bank_mask:0xf
	v_pk_mul_f32 v[26:27], v[26:27], v[170:171]
	v_add_f32_dpp v28, v28, v28 quad_perm:[2,3,0,1] row_mask:0xf bank_mask:0xf
	v_add_f32_dpp v32, v32, v32 quad_perm:[2,3,0,1] row_mask:0xf bank_mask:0xf
	v_pk_fma_f32 v[20:21], v[180:181], v[8:9], v[20:21] op_sel_hi:[1,0,1]
	v_mov_b32_dpp v30, v28 row_half_mirror row_mask:0xf bank_mask:0xf
	v_pk_fma_f32 v[22:23], v[182:183], v[8:9], v[22:23] op_sel_hi:[1,0,1]
	v_pk_fma_f32 v[24:25], v[180:181], v[10:11], v[24:25] op_sel_hi:[1,0,1]
	v_pk_fma_f32 v[26:27], v[182:183], v[10:11], v[26:27] op_sel_hi:[1,0,1]
	v_pk_fma_f32 v[20:21], v[88:89], v[28:29], v[20:21] op_sel_hi:[1,0,1] neg_lo:[0,1,0] neg_hi:[0,1,0]
	v_pk_fma_f32 v[22:23], v[90:91], v[28:29], v[22:23] op_sel_hi:[1,0,1] neg_lo:[0,1,0] neg_hi:[0,1,0]
	v_pk_fma_f32 v[24:25], v[88:89], v[30:31], v[24:25] op_sel_hi:[1,0,1] neg_lo:[0,1,0] neg_hi:[0,1,0]
	v_pk_fma_f32 v[26:27], v[90:91], v[30:31], v[26:27] op_sel_hi:[1,0,1] neg_lo:[0,1,0] neg_hi:[0,1,0]
	v_add_f32_e32 v39, v32, v9
	ds_write_b32 v102, v39 offset:1664
	ds_read_b128 v[144:147], v195 offset:4096
	ds_read_b128 v[156:159], v195 offset:12288
	ds_read_b128 v[168:171], v195 offset:28672
	ds_read_b128 v[180:183], v195 offset:20480
	ds_read_b128 v[88:91], v195 offset:36864
	ds_read_b64 v[8:9], v196 offset:8192
	ds_read_b64 v[10:11], v36 offset:8192
	s_waitcnt lgkmcnt(15)
	v_pk_mul_f32 v[46:47], v[24:25], v[148:149] op_sel_hi:[0,1]
	v_pk_mul_f32 v[34:35], v[20:21], v[148:149] op_sel_hi:[0,1]
	v_pk_fma_f32 v[46:47], v[24:25], v[150:151], v[46:47] op_sel:[1,0,0] op_sel_hi:[1,1,1]
	v_pk_fma_f32 v[34:35], v[20:21], v[150:151], v[34:35] op_sel:[1,0,0] op_sel_hi:[1,1,1]
	v_pk_fma_f32 v[46:47], v[26:27], v[160:161], v[46:47] op_sel_hi:[0,1,1]
	v_pk_fma_f32 v[34:35], v[22:23], v[160:161], v[34:35] op_sel_hi:[0,1,1]
	v_pk_fma_f32 v[46:47], v[26:27], v[162:163], v[46:47] op_sel:[1,0,0] op_sel_hi:[1,1,1]
	v_pk_fma_f32 v[34:35], v[22:23], v[162:163], v[34:35] op_sel:[1,0,0] op_sel_hi:[1,1,1]
	v_pk_mul_f32 v[20:21], v[20:21], v[172:173]
	v_add_f32_dpp v28, v46, v34 row_half_mirror row_mask:0xf bank_mask:0xf
	v_add_f32_dpp v32, v47, v35 row_half_mirror row_mask:0xf bank_mask:0xf
	v_pk_mul_f32 v[22:23], v[22:23], v[174:175]
	v_add_f32_dpp v28, v28, v28 row_ror:8 row_mask:0xf bank_mask:0xf
	v_add_f32_dpp v32, v32, v32 row_ror:8 row_mask:0xf bank_mask:0xf
	v_pk_mul_f32 v[24:25], v[24:25], v[172:173]
	v_add_f32_dpp v28, v28, v28 quad_perm:[1,0,3,2] row_mask:0xf bank_mask:0xf
	v_add_f32_dpp v32, v32, v32 quad_perm:[1,0,3,2] row_mask:0xf bank_mask:0xf
	v_pk_mul_f32 v[26:27], v[26:27], v[174:175]
	v_add_f32_dpp v28, v28, v28 quad_perm:[2,3,0,1] row_mask:0xf bank_mask:0xf
	v_add_f32_dpp v32, v32, v32 quad_perm:[2,3,0,1] row_mask:0xf bank_mask:0xf
	v_pk_fma_f32 v[20:21], v[184:185], v[12:13], v[20:21] op_sel_hi:[1,0,1]
	v_mov_b32_dpp v30, v28 row_half_mirror row_mask:0xf bank_mask:0xf
	v_pk_fma_f32 v[22:23], v[186:187], v[12:13], v[22:23] op_sel_hi:[1,0,1]
	v_pk_fma_f32 v[24:25], v[184:185], v[14:15], v[24:25] op_sel_hi:[1,0,1]
	v_pk_fma_f32 v[26:27], v[186:187], v[14:15], v[26:27] op_sel_hi:[1,0,1]
	v_pk_fma_f32 v[20:21], v[92:93], v[28:29], v[20:21] op_sel_hi:[1,0,1] neg_lo:[0,1,0] neg_hi:[0,1,0]
	v_pk_fma_f32 v[22:23], v[94:95], v[28:29], v[22:23] op_sel_hi:[1,0,1] neg_lo:[0,1,0] neg_hi:[0,1,0]
	v_pk_fma_f32 v[24:25], v[92:93], v[30:31], v[24:25] op_sel_hi:[1,0,1] neg_lo:[0,1,0] neg_hi:[0,1,0]
	v_pk_fma_f32 v[26:27], v[94:95], v[30:31], v[26:27] op_sel_hi:[1,0,1] neg_lo:[0,1,0] neg_hi:[0,1,0]
	v_add_f32_e32 v39, v32, v13
	ds_write_b32 v102, v39 offset:1792
	ds_read_b128 v[148:151], v195 offset:4352
	ds_read_b128 v[160:163], v195 offset:12544
	ds_read_b128 v[172:175], v195 offset:28928
	ds_read_b128 v[184:187], v195 offset:20736
	ds_read_b128 v[92:95], v195 offset:37120
	ds_read_b64 v[12:13], v196 offset:8704
	ds_read_b64 v[14:15], v36 offset:8704
	s_waitcnt lgkmcnt(15)
	v_pk_mul_f32 v[46:47], v[24:25], v[140:141] op_sel_hi:[0,1]
	v_pk_mul_f32 v[34:35], v[20:21], v[140:141] op_sel_hi:[0,1]
	v_pk_fma_f32 v[46:47], v[24:25], v[142:143], v[46:47] op_sel:[1,0,0] op_sel_hi:[1,1,1]
	v_pk_fma_f32 v[34:35], v[20:21], v[142:143], v[34:35] op_sel:[1,0,0] op_sel_hi:[1,1,1]
	v_pk_fma_f32 v[46:47], v[26:27], v[152:153], v[46:47] op_sel_hi:[0,1,1]
	v_pk_fma_f32 v[34:35], v[22:23], v[152:153], v[34:35] op_sel_hi:[0,1,1]
	v_pk_fma_f32 v[46:47], v[26:27], v[154:155], v[46:47] op_sel:[1,0,0] op_sel_hi:[1,1,1]
	v_pk_fma_f32 v[34:35], v[22:23], v[154:155], v[34:35] op_sel:[1,0,0] op_sel_hi:[1,1,1]
	v_pk_mul_f32 v[20:21], v[20:21], v[164:165]
	v_add_f32_dpp v28, v46, v34 row_half_mirror row_mask:0xf bank_mask:0xf
	v_add_f32_dpp v32, v47, v35 row_half_mirror row_mask:0xf bank_mask:0xf
	v_pk_mul_f32 v[22:23], v[22:23], v[166:167]
	v_add_f32_dpp v28, v28, v28 row_ror:8 row_mask:0xf bank_mask:0xf
	v_add_f32_dpp v32, v32, v32 row_ror:8 row_mask:0xf bank_mask:0xf
	v_pk_mul_f32 v[24:25], v[24:25], v[164:165]
	v_add_f32_dpp v28, v28, v28 quad_perm:[1,0,3,2] row_mask:0xf bank_mask:0xf
	v_add_f32_dpp v32, v32, v32 quad_perm:[1,0,3,2] row_mask:0xf bank_mask:0xf
	v_pk_mul_f32 v[26:27], v[26:27], v[166:167]
	v_add_f32_dpp v28, v28, v28 quad_perm:[2,3,0,1] row_mask:0xf bank_mask:0xf
	v_add_f32_dpp v32, v32, v32 quad_perm:[2,3,0,1] row_mask:0xf bank_mask:0xf
	v_pk_fma_f32 v[20:21], v[176:177], v[4:5], v[20:21] op_sel_hi:[1,0,1]
	v_mov_b32_dpp v30, v28 row_half_mirror row_mask:0xf bank_mask:0xf
	v_pk_fma_f32 v[22:23], v[178:179], v[4:5], v[22:23] op_sel_hi:[1,0,1]
	v_pk_fma_f32 v[24:25], v[176:177], v[6:7], v[24:25] op_sel_hi:[1,0,1]
	v_pk_fma_f32 v[26:27], v[178:179], v[6:7], v[26:27] op_sel_hi:[1,0,1]
	v_pk_fma_f32 v[20:21], v[84:85], v[28:29], v[20:21] op_sel_hi:[1,0,1] neg_lo:[0,1,0] neg_hi:[0,1,0]
	v_pk_fma_f32 v[22:23], v[86:87], v[28:29], v[22:23] op_sel_hi:[1,0,1] neg_lo:[0,1,0] neg_hi:[0,1,0]
	v_pk_fma_f32 v[24:25], v[84:85], v[30:31], v[24:25] op_sel_hi:[1,0,1] neg_lo:[0,1,0] neg_hi:[0,1,0]
	v_pk_fma_f32 v[26:27], v[86:87], v[30:31], v[26:27] op_sel_hi:[1,0,1] neg_lo:[0,1,0] neg_hi:[0,1,0]
	v_add_f32_e32 v39, v32, v5
	ds_write_b32 v102, v39 offset:1920
	ds_read_b128 v[140:143], v195 offset:4608
	ds_read_b128 v[152:155], v195 offset:12800
	ds_read_b128 v[164:167], v195 offset:29184
	ds_read_b128 v[176:179], v195 offset:20992
	ds_read_b128 v[84:87], v195 offset:37376
	ds_read_b64 v[4:5], v196 offset:9216
	ds_read_b64 v[6:7], v36 offset:9216
	s_waitcnt lgkmcnt(15)
	v_pk_mul_f32 v[46:47], v[24:25], v[144:145] op_sel_hi:[0,1]
	v_pk_mul_f32 v[34:35], v[20:21], v[144:145] op_sel_hi:[0,1]
	v_pk_fma_f32 v[46:47], v[24:25], v[146:147], v[46:47] op_sel:[1,0,0] op_sel_hi:[1,1,1]
	v_pk_fma_f32 v[34:35], v[20:21], v[146:147], v[34:35] op_sel:[1,0,0] op_sel_hi:[1,1,1]
	v_pk_fma_f32 v[46:47], v[26:27], v[156:157], v[46:47] op_sel_hi:[0,1,1]
	v_pk_fma_f32 v[34:35], v[22:23], v[156:157], v[34:35] op_sel_hi:[0,1,1]
	v_pk_fma_f32 v[46:47], v[26:27], v[158:159], v[46:47] op_sel:[1,0,0] op_sel_hi:[1,1,1]
	v_pk_fma_f32 v[34:35], v[22:23], v[158:159], v[34:35] op_sel:[1,0,0] op_sel_hi:[1,1,1]
	v_pk_mul_f32 v[20:21], v[20:21], v[168:169]
	v_add_f32_dpp v28, v46, v34 row_half_mirror row_mask:0xf bank_mask:0xf
	v_add_f32_dpp v32, v47, v35 row_half_mirror row_mask:0xf bank_mask:0xf
	v_pk_mul_f32 v[22:23], v[22:23], v[170:171]
	v_add_f32_dpp v28, v28, v28 row_ror:8 row_mask:0xf bank_mask:0xf
	v_add_f32_dpp v32, v32, v32 row_ror:8 row_mask:0xf bank_mask:0xf
	v_pk_mul_f32 v[24:25], v[24:25], v[168:169]
	v_add_f32_dpp v28, v28, v28 quad_perm:[1,0,3,2] row_mask:0xf bank_mask:0xf
	v_add_f32_dpp v32, v32, v32 quad_perm:[1,0,3,2] row_mask:0xf bank_mask:0xf
	v_pk_mul_f32 v[26:27], v[26:27], v[170:171]
	v_add_f32_dpp v28, v28, v28 quad_perm:[2,3,0,1] row_mask:0xf bank_mask:0xf
	v_add_f32_dpp v32, v32, v32 quad_perm:[2,3,0,1] row_mask:0xf bank_mask:0xf
	v_pk_fma_f32 v[20:21], v[180:181], v[8:9], v[20:21] op_sel_hi:[1,0,1]
	v_mov_b32_dpp v30, v28 row_half_mirror row_mask:0xf bank_mask:0xf
	v_pk_fma_f32 v[22:23], v[182:183], v[8:9], v[22:23] op_sel_hi:[1,0,1]
	v_pk_fma_f32 v[24:25], v[180:181], v[10:11], v[24:25] op_sel_hi:[1,0,1]
	v_pk_fma_f32 v[26:27], v[182:183], v[10:11], v[26:27] op_sel_hi:[1,0,1]
	v_pk_fma_f32 v[20:21], v[88:89], v[28:29], v[20:21] op_sel_hi:[1,0,1] neg_lo:[0,1,0] neg_hi:[0,1,0]
	v_pk_fma_f32 v[22:23], v[90:91], v[28:29], v[22:23] op_sel_hi:[1,0,1] neg_lo:[0,1,0] neg_hi:[0,1,0]
	v_pk_fma_f32 v[24:25], v[88:89], v[30:31], v[24:25] op_sel_hi:[1,0,1] neg_lo:[0,1,0] neg_hi:[0,1,0]
	v_pk_fma_f32 v[26:27], v[90:91], v[30:31], v[26:27] op_sel_hi:[1,0,1] neg_lo:[0,1,0] neg_hi:[0,1,0]
	v_add_f32_e32 v39, v32, v9
	ds_write_b32 v102, v39 offset:2048
	ds_read_b128 v[144:147], v195 offset:4864
	ds_read_b128 v[156:159], v195 offset:13056
	ds_read_b128 v[168:171], v195 offset:29440
	ds_read_b128 v[180:183], v195 offset:21248
	ds_read_b128 v[88:91], v195 offset:37632
	ds_read_b64 v[8:9], v196 offset:9728
	ds_read_b64 v[10:11], v36 offset:9728
	s_waitcnt lgkmcnt(15)
	v_pk_mul_f32 v[46:47], v[24:25], v[148:149] op_sel_hi:[0,1]
	v_pk_mul_f32 v[34:35], v[20:21], v[148:149] op_sel_hi:[0,1]
	v_pk_fma_f32 v[46:47], v[24:25], v[150:151], v[46:47] op_sel:[1,0,0] op_sel_hi:[1,1,1]
	v_pk_fma_f32 v[34:35], v[20:21], v[150:151], v[34:35] op_sel:[1,0,0] op_sel_hi:[1,1,1]
	v_pk_fma_f32 v[46:47], v[26:27], v[160:161], v[46:47] op_sel_hi:[0,1,1]
	v_pk_fma_f32 v[34:35], v[22:23], v[160:161], v[34:35] op_sel_hi:[0,1,1]
	v_pk_fma_f32 v[46:47], v[26:27], v[162:163], v[46:47] op_sel:[1,0,0] op_sel_hi:[1,1,1]
	v_pk_fma_f32 v[34:35], v[22:23], v[162:163], v[34:35] op_sel:[1,0,0] op_sel_hi:[1,1,1]
	v_pk_mul_f32 v[20:21], v[20:21], v[172:173]
	v_add_f32_dpp v28, v46, v34 row_half_mirror row_mask:0xf bank_mask:0xf
	v_add_f32_dpp v32, v47, v35 row_half_mirror row_mask:0xf bank_mask:0xf
	v_pk_mul_f32 v[22:23], v[22:23], v[174:175]
	v_add_f32_dpp v28, v28, v28 row_ror:8 row_mask:0xf bank_mask:0xf
	v_add_f32_dpp v32, v32, v32 row_ror:8 row_mask:0xf bank_mask:0xf
	v_pk_mul_f32 v[24:25], v[24:25], v[172:173]
	v_add_f32_dpp v28, v28, v28 quad_perm:[1,0,3,2] row_mask:0xf bank_mask:0xf
	v_add_f32_dpp v32, v32, v32 quad_perm:[1,0,3,2] row_mask:0xf bank_mask:0xf
	v_pk_mul_f32 v[26:27], v[26:27], v[174:175]
	v_add_f32_dpp v28, v28, v28 quad_perm:[2,3,0,1] row_mask:0xf bank_mask:0xf
	v_add_f32_dpp v32, v32, v32 quad_perm:[2,3,0,1] row_mask:0xf bank_mask:0xf
	v_pk_fma_f32 v[20:21], v[184:185], v[12:13], v[20:21] op_sel_hi:[1,0,1]
	v_mov_b32_dpp v30, v28 row_half_mirror row_mask:0xf bank_mask:0xf
	v_pk_fma_f32 v[22:23], v[186:187], v[12:13], v[22:23] op_sel_hi:[1,0,1]
	v_pk_fma_f32 v[24:25], v[184:185], v[14:15], v[24:25] op_sel_hi:[1,0,1]
	v_pk_fma_f32 v[26:27], v[186:187], v[14:15], v[26:27] op_sel_hi:[1,0,1]
	v_pk_fma_f32 v[20:21], v[92:93], v[28:29], v[20:21] op_sel_hi:[1,0,1] neg_lo:[0,1,0] neg_hi:[0,1,0]
	v_pk_fma_f32 v[22:23], v[94:95], v[28:29], v[22:23] op_sel_hi:[1,0,1] neg_lo:[0,1,0] neg_hi:[0,1,0]
	v_pk_fma_f32 v[24:25], v[92:93], v[30:31], v[24:25] op_sel_hi:[1,0,1] neg_lo:[0,1,0] neg_hi:[0,1,0]
	v_pk_fma_f32 v[26:27], v[94:95], v[30:31], v[26:27] op_sel_hi:[1,0,1] neg_lo:[0,1,0] neg_hi:[0,1,0]
	v_add_f32_e32 v39, v32, v13
	ds_write_b32 v102, v39 offset:2176
	ds_read_b128 v[148:151], v195 offset:5120
	ds_read_b128 v[160:163], v195 offset:13312
	ds_read_b128 v[172:175], v195 offset:29696
	ds_read_b128 v[184:187], v195 offset:21504
	ds_read_b128 v[92:95], v195 offset:37888
	ds_read_b64 v[12:13], v196 offset:10240
	ds_read_b64 v[14:15], v36 offset:10240
	s_waitcnt lgkmcnt(15)
	v_pk_mul_f32 v[46:47], v[24:25], v[140:141] op_sel_hi:[0,1]
	v_pk_mul_f32 v[34:35], v[20:21], v[140:141] op_sel_hi:[0,1]
	v_pk_fma_f32 v[46:47], v[24:25], v[142:143], v[46:47] op_sel:[1,0,0] op_sel_hi:[1,1,1]
	v_pk_fma_f32 v[34:35], v[20:21], v[142:143], v[34:35] op_sel:[1,0,0] op_sel_hi:[1,1,1]
	v_pk_fma_f32 v[46:47], v[26:27], v[152:153], v[46:47] op_sel_hi:[0,1,1]
	v_pk_fma_f32 v[34:35], v[22:23], v[152:153], v[34:35] op_sel_hi:[0,1,1]
	v_pk_fma_f32 v[46:47], v[26:27], v[154:155], v[46:47] op_sel:[1,0,0] op_sel_hi:[1,1,1]
	v_pk_fma_f32 v[34:35], v[22:23], v[154:155], v[34:35] op_sel:[1,0,0] op_sel_hi:[1,1,1]
	v_pk_mul_f32 v[20:21], v[20:21], v[164:165]
	v_add_f32_dpp v28, v46, v34 row_half_mirror row_mask:0xf bank_mask:0xf
	v_add_f32_dpp v32, v47, v35 row_half_mirror row_mask:0xf bank_mask:0xf
	v_pk_mul_f32 v[22:23], v[22:23], v[166:167]
	v_add_f32_dpp v28, v28, v28 row_ror:8 row_mask:0xf bank_mask:0xf
	v_add_f32_dpp v32, v32, v32 row_ror:8 row_mask:0xf bank_mask:0xf
	v_pk_mul_f32 v[24:25], v[24:25], v[164:165]
	v_add_f32_dpp v28, v28, v28 quad_perm:[1,0,3,2] row_mask:0xf bank_mask:0xf
	v_add_f32_dpp v32, v32, v32 quad_perm:[1,0,3,2] row_mask:0xf bank_mask:0xf
	v_pk_mul_f32 v[26:27], v[26:27], v[166:167]
	v_add_f32_dpp v28, v28, v28 quad_perm:[2,3,0,1] row_mask:0xf bank_mask:0xf
	v_add_f32_dpp v32, v32, v32 quad_perm:[2,3,0,1] row_mask:0xf bank_mask:0xf
	v_pk_fma_f32 v[20:21], v[176:177], v[4:5], v[20:21] op_sel_hi:[1,0,1]
	v_mov_b32_dpp v30, v28 row_half_mirror row_mask:0xf bank_mask:0xf
	v_pk_fma_f32 v[22:23], v[178:179], v[4:5], v[22:23] op_sel_hi:[1,0,1]
	v_pk_fma_f32 v[24:25], v[176:177], v[6:7], v[24:25] op_sel_hi:[1,0,1]
	v_pk_fma_f32 v[26:27], v[178:179], v[6:7], v[26:27] op_sel_hi:[1,0,1]
	v_pk_fma_f32 v[20:21], v[84:85], v[28:29], v[20:21] op_sel_hi:[1,0,1] neg_lo:[0,1,0] neg_hi:[0,1,0]
	v_pk_fma_f32 v[22:23], v[86:87], v[28:29], v[22:23] op_sel_hi:[1,0,1] neg_lo:[0,1,0] neg_hi:[0,1,0]
	v_pk_fma_f32 v[24:25], v[84:85], v[30:31], v[24:25] op_sel_hi:[1,0,1] neg_lo:[0,1,0] neg_hi:[0,1,0]
	v_pk_fma_f32 v[26:27], v[86:87], v[30:31], v[26:27] op_sel_hi:[1,0,1] neg_lo:[0,1,0] neg_hi:[0,1,0]
	v_add_f32_e32 v39, v32, v5
	ds_write_b32 v102, v39 offset:2304
	ds_read_b128 v[140:143], v195 offset:5376
	ds_read_b128 v[152:155], v195 offset:13568
	ds_read_b128 v[164:167], v195 offset:29952
	ds_read_b128 v[176:179], v195 offset:21760
	ds_read_b128 v[84:87], v195 offset:38144
	ds_read_b64 v[4:5], v196 offset:10752
	ds_read_b64 v[6:7], v36 offset:10752
	s_waitcnt lgkmcnt(15)
	v_pk_mul_f32 v[46:47], v[24:25], v[144:145] op_sel_hi:[0,1]
	v_pk_mul_f32 v[34:35], v[20:21], v[144:145] op_sel_hi:[0,1]
	v_pk_fma_f32 v[46:47], v[24:25], v[146:147], v[46:47] op_sel:[1,0,0] op_sel_hi:[1,1,1]
	v_pk_fma_f32 v[34:35], v[20:21], v[146:147], v[34:35] op_sel:[1,0,0] op_sel_hi:[1,1,1]
	v_pk_fma_f32 v[46:47], v[26:27], v[156:157], v[46:47] op_sel_hi:[0,1,1]
	v_pk_fma_f32 v[34:35], v[22:23], v[156:157], v[34:35] op_sel_hi:[0,1,1]
	v_pk_fma_f32 v[46:47], v[26:27], v[158:159], v[46:47] op_sel:[1,0,0] op_sel_hi:[1,1,1]
	v_pk_fma_f32 v[34:35], v[22:23], v[158:159], v[34:35] op_sel:[1,0,0] op_sel_hi:[1,1,1]
	v_pk_mul_f32 v[20:21], v[20:21], v[168:169]
	v_add_f32_dpp v28, v46, v34 row_half_mirror row_mask:0xf bank_mask:0xf
	v_add_f32_dpp v32, v47, v35 row_half_mirror row_mask:0xf bank_mask:0xf
	v_pk_mul_f32 v[22:23], v[22:23], v[170:171]
	v_add_f32_dpp v28, v28, v28 row_ror:8 row_mask:0xf bank_mask:0xf
	v_add_f32_dpp v32, v32, v32 row_ror:8 row_mask:0xf bank_mask:0xf
	v_pk_mul_f32 v[24:25], v[24:25], v[168:169]
	v_add_f32_dpp v28, v28, v28 quad_perm:[1,0,3,2] row_mask:0xf bank_mask:0xf
	v_add_f32_dpp v32, v32, v32 quad_perm:[1,0,3,2] row_mask:0xf bank_mask:0xf
	v_pk_mul_f32 v[26:27], v[26:27], v[170:171]
	v_add_f32_dpp v28, v28, v28 quad_perm:[2,3,0,1] row_mask:0xf bank_mask:0xf
	v_add_f32_dpp v32, v32, v32 quad_perm:[2,3,0,1] row_mask:0xf bank_mask:0xf
	v_pk_fma_f32 v[20:21], v[180:181], v[8:9], v[20:21] op_sel_hi:[1,0,1]
	v_mov_b32_dpp v30, v28 row_half_mirror row_mask:0xf bank_mask:0xf
	v_pk_fma_f32 v[22:23], v[182:183], v[8:9], v[22:23] op_sel_hi:[1,0,1]
	v_pk_fma_f32 v[24:25], v[180:181], v[10:11], v[24:25] op_sel_hi:[1,0,1]
	v_pk_fma_f32 v[26:27], v[182:183], v[10:11], v[26:27] op_sel_hi:[1,0,1]
	v_pk_fma_f32 v[20:21], v[88:89], v[28:29], v[20:21] op_sel_hi:[1,0,1] neg_lo:[0,1,0] neg_hi:[0,1,0]
	v_pk_fma_f32 v[22:23], v[90:91], v[28:29], v[22:23] op_sel_hi:[1,0,1] neg_lo:[0,1,0] neg_hi:[0,1,0]
	v_pk_fma_f32 v[24:25], v[88:89], v[30:31], v[24:25] op_sel_hi:[1,0,1] neg_lo:[0,1,0] neg_hi:[0,1,0]
	v_pk_fma_f32 v[26:27], v[90:91], v[30:31], v[26:27] op_sel_hi:[1,0,1] neg_lo:[0,1,0] neg_hi:[0,1,0]
	v_add_f32_e32 v39, v32, v9
	ds_write_b32 v102, v39 offset:2432
	ds_read_b128 v[144:147], v195 offset:5632
	ds_read_b128 v[156:159], v195 offset:13824
	ds_read_b128 v[168:171], v195 offset:30208
	ds_read_b128 v[180:183], v195 offset:22016
	ds_read_b128 v[88:91], v195 offset:38400
	ds_read_b64 v[8:9], v196 offset:11264
	ds_read_b64 v[10:11], v36 offset:11264
	s_waitcnt lgkmcnt(15)
	v_pk_mul_f32 v[46:47], v[24:25], v[148:149] op_sel_hi:[0,1]
	v_pk_mul_f32 v[34:35], v[20:21], v[148:149] op_sel_hi:[0,1]
	v_pk_fma_f32 v[46:47], v[24:25], v[150:151], v[46:47] op_sel:[1,0,0] op_sel_hi:[1,1,1]
	v_pk_fma_f32 v[34:35], v[20:21], v[150:151], v[34:35] op_sel:[1,0,0] op_sel_hi:[1,1,1]
	v_pk_fma_f32 v[46:47], v[26:27], v[160:161], v[46:47] op_sel_hi:[0,1,1]
	v_pk_fma_f32 v[34:35], v[22:23], v[160:161], v[34:35] op_sel_hi:[0,1,1]
	v_pk_fma_f32 v[46:47], v[26:27], v[162:163], v[46:47] op_sel:[1,0,0] op_sel_hi:[1,1,1]
	v_pk_fma_f32 v[34:35], v[22:23], v[162:163], v[34:35] op_sel:[1,0,0] op_sel_hi:[1,1,1]
	v_pk_mul_f32 v[20:21], v[20:21], v[172:173]
	v_add_f32_dpp v28, v46, v34 row_half_mirror row_mask:0xf bank_mask:0xf
	v_add_f32_dpp v32, v47, v35 row_half_mirror row_mask:0xf bank_mask:0xf
	v_pk_mul_f32 v[22:23], v[22:23], v[174:175]
	v_add_f32_dpp v28, v28, v28 row_ror:8 row_mask:0xf bank_mask:0xf
	v_add_f32_dpp v32, v32, v32 row_ror:8 row_mask:0xf bank_mask:0xf
	v_pk_mul_f32 v[24:25], v[24:25], v[172:173]
	v_add_f32_dpp v28, v28, v28 quad_perm:[1,0,3,2] row_mask:0xf bank_mask:0xf
	v_add_f32_dpp v32, v32, v32 quad_perm:[1,0,3,2] row_mask:0xf bank_mask:0xf
	v_pk_mul_f32 v[26:27], v[26:27], v[174:175]
	v_add_f32_dpp v28, v28, v28 quad_perm:[2,3,0,1] row_mask:0xf bank_mask:0xf
	v_add_f32_dpp v32, v32, v32 quad_perm:[2,3,0,1] row_mask:0xf bank_mask:0xf
	v_pk_fma_f32 v[20:21], v[184:185], v[12:13], v[20:21] op_sel_hi:[1,0,1]
	v_mov_b32_dpp v30, v28 row_half_mirror row_mask:0xf bank_mask:0xf
	v_pk_fma_f32 v[22:23], v[186:187], v[12:13], v[22:23] op_sel_hi:[1,0,1]
	v_pk_fma_f32 v[24:25], v[184:185], v[14:15], v[24:25] op_sel_hi:[1,0,1]
	v_pk_fma_f32 v[26:27], v[186:187], v[14:15], v[26:27] op_sel_hi:[1,0,1]
	v_pk_fma_f32 v[20:21], v[92:93], v[28:29], v[20:21] op_sel_hi:[1,0,1] neg_lo:[0,1,0] neg_hi:[0,1,0]
	v_pk_fma_f32 v[22:23], v[94:95], v[28:29], v[22:23] op_sel_hi:[1,0,1] neg_lo:[0,1,0] neg_hi:[0,1,0]
	v_pk_fma_f32 v[24:25], v[92:93], v[30:31], v[24:25] op_sel_hi:[1,0,1] neg_lo:[0,1,0] neg_hi:[0,1,0]
	v_pk_fma_f32 v[26:27], v[94:95], v[30:31], v[26:27] op_sel_hi:[1,0,1] neg_lo:[0,1,0] neg_hi:[0,1,0]
	v_add_f32_e32 v39, v32, v13
	ds_write_b32 v102, v39 offset:2560
	ds_read_b128 v[148:151], v195 offset:5888
	ds_read_b128 v[160:163], v195 offset:14080
	ds_read_b128 v[172:175], v195 offset:30464
	ds_read_b128 v[184:187], v195 offset:22272
	ds_read_b128 v[92:95], v195 offset:38656
	ds_read_b64 v[12:13], v196 offset:11776
	ds_read_b64 v[14:15], v36 offset:11776
	s_waitcnt lgkmcnt(15)
	v_pk_mul_f32 v[46:47], v[24:25], v[140:141] op_sel_hi:[0,1]
	v_pk_mul_f32 v[34:35], v[20:21], v[140:141] op_sel_hi:[0,1]
	v_pk_fma_f32 v[46:47], v[24:25], v[142:143], v[46:47] op_sel:[1,0,0] op_sel_hi:[1,1,1]
	v_pk_fma_f32 v[34:35], v[20:21], v[142:143], v[34:35] op_sel:[1,0,0] op_sel_hi:[1,1,1]
	v_pk_fma_f32 v[46:47], v[26:27], v[152:153], v[46:47] op_sel_hi:[0,1,1]
	v_pk_fma_f32 v[34:35], v[22:23], v[152:153], v[34:35] op_sel_hi:[0,1,1]
	v_pk_fma_f32 v[46:47], v[26:27], v[154:155], v[46:47] op_sel:[1,0,0] op_sel_hi:[1,1,1]
	v_pk_fma_f32 v[34:35], v[22:23], v[154:155], v[34:35] op_sel:[1,0,0] op_sel_hi:[1,1,1]
	v_pk_mul_f32 v[20:21], v[20:21], v[164:165]
	v_add_f32_dpp v28, v46, v34 row_half_mirror row_mask:0xf bank_mask:0xf
	v_add_f32_dpp v32, v47, v35 row_half_mirror row_mask:0xf bank_mask:0xf
	v_pk_mul_f32 v[22:23], v[22:23], v[166:167]
	v_add_f32_dpp v28, v28, v28 row_ror:8 row_mask:0xf bank_mask:0xf
	v_add_f32_dpp v32, v32, v32 row_ror:8 row_mask:0xf bank_mask:0xf
	v_pk_mul_f32 v[24:25], v[24:25], v[164:165]
	v_add_f32_dpp v28, v28, v28 quad_perm:[1,0,3,2] row_mask:0xf bank_mask:0xf
	v_add_f32_dpp v32, v32, v32 quad_perm:[1,0,3,2] row_mask:0xf bank_mask:0xf
	v_pk_mul_f32 v[26:27], v[26:27], v[166:167]
	v_add_f32_dpp v28, v28, v28 quad_perm:[2,3,0,1] row_mask:0xf bank_mask:0xf
	v_add_f32_dpp v32, v32, v32 quad_perm:[2,3,0,1] row_mask:0xf bank_mask:0xf
	v_pk_fma_f32 v[20:21], v[176:177], v[4:5], v[20:21] op_sel_hi:[1,0,1]
	v_mov_b32_dpp v30, v28 row_half_mirror row_mask:0xf bank_mask:0xf
	v_pk_fma_f32 v[22:23], v[178:179], v[4:5], v[22:23] op_sel_hi:[1,0,1]
	v_pk_fma_f32 v[24:25], v[176:177], v[6:7], v[24:25] op_sel_hi:[1,0,1]
	v_pk_fma_f32 v[26:27], v[178:179], v[6:7], v[26:27] op_sel_hi:[1,0,1]
	v_pk_fma_f32 v[20:21], v[84:85], v[28:29], v[20:21] op_sel_hi:[1,0,1] neg_lo:[0,1,0] neg_hi:[0,1,0]
	v_pk_fma_f32 v[22:23], v[86:87], v[28:29], v[22:23] op_sel_hi:[1,0,1] neg_lo:[0,1,0] neg_hi:[0,1,0]
	v_pk_fma_f32 v[24:25], v[84:85], v[30:31], v[24:25] op_sel_hi:[1,0,1] neg_lo:[0,1,0] neg_hi:[0,1,0]
	v_pk_fma_f32 v[26:27], v[86:87], v[30:31], v[26:27] op_sel_hi:[1,0,1] neg_lo:[0,1,0] neg_hi:[0,1,0]
	v_add_f32_e32 v39, v32, v5
	ds_write_b32 v102, v39 offset:2688
	ds_read_b128 v[140:143], v195 offset:6144
	ds_read_b128 v[152:155], v195 offset:14336
	ds_read_b128 v[164:167], v195 offset:30720
	ds_read_b128 v[176:179], v195 offset:22528
	ds_read_b128 v[84:87], v195 offset:38912
	ds_read_b64 v[4:5], v196 offset:12288
	ds_read_b64 v[6:7], v36 offset:12288
	s_waitcnt lgkmcnt(15)
	v_pk_mul_f32 v[46:47], v[24:25], v[144:145] op_sel_hi:[0,1]
	v_pk_mul_f32 v[34:35], v[20:21], v[144:145] op_sel_hi:[0,1]
	v_pk_fma_f32 v[46:47], v[24:25], v[146:147], v[46:47] op_sel:[1,0,0] op_sel_hi:[1,1,1]
	v_pk_fma_f32 v[34:35], v[20:21], v[146:147], v[34:35] op_sel:[1,0,0] op_sel_hi:[1,1,1]
	v_pk_fma_f32 v[46:47], v[26:27], v[156:157], v[46:47] op_sel_hi:[0,1,1]
	v_pk_fma_f32 v[34:35], v[22:23], v[156:157], v[34:35] op_sel_hi:[0,1,1]
	v_pk_fma_f32 v[46:47], v[26:27], v[158:159], v[46:47] op_sel:[1,0,0] op_sel_hi:[1,1,1]
	v_pk_fma_f32 v[34:35], v[22:23], v[158:159], v[34:35] op_sel:[1,0,0] op_sel_hi:[1,1,1]
	v_pk_mul_f32 v[20:21], v[20:21], v[168:169]
	v_add_f32_dpp v28, v46, v34 row_half_mirror row_mask:0xf bank_mask:0xf
	v_add_f32_dpp v32, v47, v35 row_half_mirror row_mask:0xf bank_mask:0xf
	v_pk_mul_f32 v[22:23], v[22:23], v[170:171]
	v_add_f32_dpp v28, v28, v28 row_ror:8 row_mask:0xf bank_mask:0xf
	v_add_f32_dpp v32, v32, v32 row_ror:8 row_mask:0xf bank_mask:0xf
	v_pk_mul_f32 v[24:25], v[24:25], v[168:169]
	v_add_f32_dpp v28, v28, v28 quad_perm:[1,0,3,2] row_mask:0xf bank_mask:0xf
	v_add_f32_dpp v32, v32, v32 quad_perm:[1,0,3,2] row_mask:0xf bank_mask:0xf
	v_pk_mul_f32 v[26:27], v[26:27], v[170:171]
	v_add_f32_dpp v28, v28, v28 quad_perm:[2,3,0,1] row_mask:0xf bank_mask:0xf
	v_add_f32_dpp v32, v32, v32 quad_perm:[2,3,0,1] row_mask:0xf bank_mask:0xf
	v_pk_fma_f32 v[20:21], v[180:181], v[8:9], v[20:21] op_sel_hi:[1,0,1]
	v_mov_b32_dpp v30, v28 row_half_mirror row_mask:0xf bank_mask:0xf
	v_pk_fma_f32 v[22:23], v[182:183], v[8:9], v[22:23] op_sel_hi:[1,0,1]
	v_pk_fma_f32 v[24:25], v[180:181], v[10:11], v[24:25] op_sel_hi:[1,0,1]
	v_pk_fma_f32 v[26:27], v[182:183], v[10:11], v[26:27] op_sel_hi:[1,0,1]
	v_pk_fma_f32 v[20:21], v[88:89], v[28:29], v[20:21] op_sel_hi:[1,0,1] neg_lo:[0,1,0] neg_hi:[0,1,0]
	v_pk_fma_f32 v[22:23], v[90:91], v[28:29], v[22:23] op_sel_hi:[1,0,1] neg_lo:[0,1,0] neg_hi:[0,1,0]
	v_pk_fma_f32 v[24:25], v[88:89], v[30:31], v[24:25] op_sel_hi:[1,0,1] neg_lo:[0,1,0] neg_hi:[0,1,0]
	v_pk_fma_f32 v[26:27], v[90:91], v[30:31], v[26:27] op_sel_hi:[1,0,1] neg_lo:[0,1,0] neg_hi:[0,1,0]
	v_add_f32_e32 v39, v32, v9
	ds_write_b32 v102, v39 offset:2816
	ds_read_b128 v[144:147], v195 offset:6400
	ds_read_b128 v[156:159], v195 offset:14592
	ds_read_b128 v[168:171], v195 offset:30976
	ds_read_b128 v[180:183], v195 offset:22784
	ds_read_b128 v[88:91], v195 offset:39168
	ds_read_b64 v[8:9], v196 offset:12800
	ds_read_b64 v[10:11], v36 offset:12800
	s_waitcnt lgkmcnt(15)
	v_pk_mul_f32 v[46:47], v[24:25], v[148:149] op_sel_hi:[0,1]
	v_pk_mul_f32 v[34:35], v[20:21], v[148:149] op_sel_hi:[0,1]
	v_pk_fma_f32 v[46:47], v[24:25], v[150:151], v[46:47] op_sel:[1,0,0] op_sel_hi:[1,1,1]
	v_pk_fma_f32 v[34:35], v[20:21], v[150:151], v[34:35] op_sel:[1,0,0] op_sel_hi:[1,1,1]
	v_pk_fma_f32 v[46:47], v[26:27], v[160:161], v[46:47] op_sel_hi:[0,1,1]
	v_pk_fma_f32 v[34:35], v[22:23], v[160:161], v[34:35] op_sel_hi:[0,1,1]
	v_pk_fma_f32 v[46:47], v[26:27], v[162:163], v[46:47] op_sel:[1,0,0] op_sel_hi:[1,1,1]
	v_pk_fma_f32 v[34:35], v[22:23], v[162:163], v[34:35] op_sel:[1,0,0] op_sel_hi:[1,1,1]
	v_pk_mul_f32 v[20:21], v[20:21], v[172:173]
	v_add_f32_dpp v28, v46, v34 row_half_mirror row_mask:0xf bank_mask:0xf
	v_add_f32_dpp v32, v47, v35 row_half_mirror row_mask:0xf bank_mask:0xf
	v_pk_mul_f32 v[22:23], v[22:23], v[174:175]
	v_add_f32_dpp v28, v28, v28 row_ror:8 row_mask:0xf bank_mask:0xf
	v_add_f32_dpp v32, v32, v32 row_ror:8 row_mask:0xf bank_mask:0xf
	v_pk_mul_f32 v[24:25], v[24:25], v[172:173]
	v_add_f32_dpp v28, v28, v28 quad_perm:[1,0,3,2] row_mask:0xf bank_mask:0xf
	v_add_f32_dpp v32, v32, v32 quad_perm:[1,0,3,2] row_mask:0xf bank_mask:0xf
	v_pk_mul_f32 v[26:27], v[26:27], v[174:175]
	v_add_f32_dpp v28, v28, v28 quad_perm:[2,3,0,1] row_mask:0xf bank_mask:0xf
	v_add_f32_dpp v32, v32, v32 quad_perm:[2,3,0,1] row_mask:0xf bank_mask:0xf
	v_pk_fma_f32 v[20:21], v[184:185], v[12:13], v[20:21] op_sel_hi:[1,0,1]
	v_mov_b32_dpp v30, v28 row_half_mirror row_mask:0xf bank_mask:0xf
	v_pk_fma_f32 v[22:23], v[186:187], v[12:13], v[22:23] op_sel_hi:[1,0,1]
	v_pk_fma_f32 v[24:25], v[184:185], v[14:15], v[24:25] op_sel_hi:[1,0,1]
	v_pk_fma_f32 v[26:27], v[186:187], v[14:15], v[26:27] op_sel_hi:[1,0,1]
	v_pk_fma_f32 v[20:21], v[92:93], v[28:29], v[20:21] op_sel_hi:[1,0,1] neg_lo:[0,1,0] neg_hi:[0,1,0]
	v_pk_fma_f32 v[22:23], v[94:95], v[28:29], v[22:23] op_sel_hi:[1,0,1] neg_lo:[0,1,0] neg_hi:[0,1,0]
	v_pk_fma_f32 v[24:25], v[92:93], v[30:31], v[24:25] op_sel_hi:[1,0,1] neg_lo:[0,1,0] neg_hi:[0,1,0]
	v_pk_fma_f32 v[26:27], v[94:95], v[30:31], v[26:27] op_sel_hi:[1,0,1] neg_lo:[0,1,0] neg_hi:[0,1,0]
	v_add_f32_e32 v39, v32, v13
	ds_write_b32 v102, v39 offset:2944
	ds_read_b128 v[148:151], v195 offset:6656
	ds_read_b128 v[160:163], v195 offset:14848
	ds_read_b128 v[172:175], v195 offset:31232
	ds_read_b128 v[184:187], v195 offset:23040
	ds_read_b128 v[92:95], v195 offset:39424
	ds_read_b64 v[12:13], v196 offset:13312
	ds_read_b64 v[14:15], v36 offset:13312
	s_waitcnt lgkmcnt(15)
	v_pk_mul_f32 v[46:47], v[24:25], v[140:141] op_sel_hi:[0,1]
	v_pk_mul_f32 v[34:35], v[20:21], v[140:141] op_sel_hi:[0,1]
	v_pk_fma_f32 v[46:47], v[24:25], v[142:143], v[46:47] op_sel:[1,0,0] op_sel_hi:[1,1,1]
	v_pk_fma_f32 v[34:35], v[20:21], v[142:143], v[34:35] op_sel:[1,0,0] op_sel_hi:[1,1,1]
	v_pk_fma_f32 v[46:47], v[26:27], v[152:153], v[46:47] op_sel_hi:[0,1,1]
	v_pk_fma_f32 v[34:35], v[22:23], v[152:153], v[34:35] op_sel_hi:[0,1,1]
	v_pk_fma_f32 v[46:47], v[26:27], v[154:155], v[46:47] op_sel:[1,0,0] op_sel_hi:[1,1,1]
	v_pk_fma_f32 v[34:35], v[22:23], v[154:155], v[34:35] op_sel:[1,0,0] op_sel_hi:[1,1,1]
	v_pk_mul_f32 v[20:21], v[20:21], v[164:165]
	v_add_f32_dpp v28, v46, v34 row_half_mirror row_mask:0xf bank_mask:0xf
	v_add_f32_dpp v32, v47, v35 row_half_mirror row_mask:0xf bank_mask:0xf
	v_pk_mul_f32 v[22:23], v[22:23], v[166:167]
	v_add_f32_dpp v28, v28, v28 row_ror:8 row_mask:0xf bank_mask:0xf
	v_add_f32_dpp v32, v32, v32 row_ror:8 row_mask:0xf bank_mask:0xf
	v_pk_mul_f32 v[24:25], v[24:25], v[164:165]
	v_add_f32_dpp v28, v28, v28 quad_perm:[1,0,3,2] row_mask:0xf bank_mask:0xf
	v_add_f32_dpp v32, v32, v32 quad_perm:[1,0,3,2] row_mask:0xf bank_mask:0xf
	v_pk_mul_f32 v[26:27], v[26:27], v[166:167]
	v_add_f32_dpp v28, v28, v28 quad_perm:[2,3,0,1] row_mask:0xf bank_mask:0xf
	v_add_f32_dpp v32, v32, v32 quad_perm:[2,3,0,1] row_mask:0xf bank_mask:0xf
	v_pk_fma_f32 v[20:21], v[176:177], v[4:5], v[20:21] op_sel_hi:[1,0,1]
	v_mov_b32_dpp v30, v28 row_half_mirror row_mask:0xf bank_mask:0xf
	v_pk_fma_f32 v[22:23], v[178:179], v[4:5], v[22:23] op_sel_hi:[1,0,1]
	v_pk_fma_f32 v[24:25], v[176:177], v[6:7], v[24:25] op_sel_hi:[1,0,1]
	v_pk_fma_f32 v[26:27], v[178:179], v[6:7], v[26:27] op_sel_hi:[1,0,1]
	v_pk_fma_f32 v[20:21], v[84:85], v[28:29], v[20:21] op_sel_hi:[1,0,1] neg_lo:[0,1,0] neg_hi:[0,1,0]
	v_pk_fma_f32 v[22:23], v[86:87], v[28:29], v[22:23] op_sel_hi:[1,0,1] neg_lo:[0,1,0] neg_hi:[0,1,0]
	v_pk_fma_f32 v[24:25], v[84:85], v[30:31], v[24:25] op_sel_hi:[1,0,1] neg_lo:[0,1,0] neg_hi:[0,1,0]
	v_pk_fma_f32 v[26:27], v[86:87], v[30:31], v[26:27] op_sel_hi:[1,0,1] neg_lo:[0,1,0] neg_hi:[0,1,0]
	v_add_f32_e32 v39, v32, v5
	ds_write_b32 v102, v39 offset:3072
	ds_read_b128 v[140:143], v195 offset:6912
	ds_read_b128 v[152:155], v195 offset:15104
	ds_read_b128 v[164:167], v195 offset:31488
	ds_read_b128 v[176:179], v195 offset:23296
	ds_read_b128 v[84:87], v195 offset:39680
	ds_read_b64 v[4:5], v196 offset:13824
	ds_read_b64 v[6:7], v36 offset:13824
	s_waitcnt lgkmcnt(15)
	v_pk_mul_f32 v[46:47], v[24:25], v[144:145] op_sel_hi:[0,1]
	v_pk_mul_f32 v[34:35], v[20:21], v[144:145] op_sel_hi:[0,1]
	v_pk_fma_f32 v[46:47], v[24:25], v[146:147], v[46:47] op_sel:[1,0,0] op_sel_hi:[1,1,1]
	v_pk_fma_f32 v[34:35], v[20:21], v[146:147], v[34:35] op_sel:[1,0,0] op_sel_hi:[1,1,1]
	v_pk_fma_f32 v[46:47], v[26:27], v[156:157], v[46:47] op_sel_hi:[0,1,1]
	v_pk_fma_f32 v[34:35], v[22:23], v[156:157], v[34:35] op_sel_hi:[0,1,1]
	v_pk_fma_f32 v[46:47], v[26:27], v[158:159], v[46:47] op_sel:[1,0,0] op_sel_hi:[1,1,1]
	v_pk_fma_f32 v[34:35], v[22:23], v[158:159], v[34:35] op_sel:[1,0,0] op_sel_hi:[1,1,1]
	v_pk_mul_f32 v[20:21], v[20:21], v[168:169]
	v_add_f32_dpp v28, v46, v34 row_half_mirror row_mask:0xf bank_mask:0xf
	v_add_f32_dpp v32, v47, v35 row_half_mirror row_mask:0xf bank_mask:0xf
	v_pk_mul_f32 v[22:23], v[22:23], v[170:171]
	v_add_f32_dpp v28, v28, v28 row_ror:8 row_mask:0xf bank_mask:0xf
	v_add_f32_dpp v32, v32, v32 row_ror:8 row_mask:0xf bank_mask:0xf
	v_pk_mul_f32 v[24:25], v[24:25], v[168:169]
	v_add_f32_dpp v28, v28, v28 quad_perm:[1,0,3,2] row_mask:0xf bank_mask:0xf
	v_add_f32_dpp v32, v32, v32 quad_perm:[1,0,3,2] row_mask:0xf bank_mask:0xf
	v_pk_mul_f32 v[26:27], v[26:27], v[170:171]
	v_add_f32_dpp v28, v28, v28 quad_perm:[2,3,0,1] row_mask:0xf bank_mask:0xf
	v_add_f32_dpp v32, v32, v32 quad_perm:[2,3,0,1] row_mask:0xf bank_mask:0xf
	v_pk_fma_f32 v[20:21], v[180:181], v[8:9], v[20:21] op_sel_hi:[1,0,1]
	v_mov_b32_dpp v30, v28 row_half_mirror row_mask:0xf bank_mask:0xf
	v_pk_fma_f32 v[22:23], v[182:183], v[8:9], v[22:23] op_sel_hi:[1,0,1]
	v_pk_fma_f32 v[24:25], v[180:181], v[10:11], v[24:25] op_sel_hi:[1,0,1]
	v_pk_fma_f32 v[26:27], v[182:183], v[10:11], v[26:27] op_sel_hi:[1,0,1]
	v_pk_fma_f32 v[20:21], v[88:89], v[28:29], v[20:21] op_sel_hi:[1,0,1] neg_lo:[0,1,0] neg_hi:[0,1,0]
	v_pk_fma_f32 v[22:23], v[90:91], v[28:29], v[22:23] op_sel_hi:[1,0,1] neg_lo:[0,1,0] neg_hi:[0,1,0]
	v_pk_fma_f32 v[24:25], v[88:89], v[30:31], v[24:25] op_sel_hi:[1,0,1] neg_lo:[0,1,0] neg_hi:[0,1,0]
	v_pk_fma_f32 v[26:27], v[90:91], v[30:31], v[26:27] op_sel_hi:[1,0,1] neg_lo:[0,1,0] neg_hi:[0,1,0]
	v_add_f32_e32 v39, v32, v9
	ds_write_b32 v102, v39 offset:3200
	ds_read_b128 v[144:147], v195 offset:7168
	ds_read_b128 v[156:159], v195 offset:15360
	ds_read_b128 v[168:171], v195 offset:31744
	ds_read_b128 v[180:183], v195 offset:23552
	ds_read_b128 v[88:91], v195 offset:39936
	ds_read_b64 v[8:9], v196 offset:14336
	ds_read_b64 v[10:11], v36 offset:14336
	s_waitcnt lgkmcnt(15)
	v_pk_mul_f32 v[46:47], v[24:25], v[148:149] op_sel_hi:[0,1]
	v_pk_mul_f32 v[34:35], v[20:21], v[148:149] op_sel_hi:[0,1]
	v_pk_fma_f32 v[46:47], v[24:25], v[150:151], v[46:47] op_sel:[1,0,0] op_sel_hi:[1,1,1]
	v_pk_fma_f32 v[34:35], v[20:21], v[150:151], v[34:35] op_sel:[1,0,0] op_sel_hi:[1,1,1]
	v_pk_fma_f32 v[46:47], v[26:27], v[160:161], v[46:47] op_sel_hi:[0,1,1]
	v_pk_fma_f32 v[34:35], v[22:23], v[160:161], v[34:35] op_sel_hi:[0,1,1]
	v_pk_fma_f32 v[46:47], v[26:27], v[162:163], v[46:47] op_sel:[1,0,0] op_sel_hi:[1,1,1]
	v_pk_fma_f32 v[34:35], v[22:23], v[162:163], v[34:35] op_sel:[1,0,0] op_sel_hi:[1,1,1]
	v_pk_mul_f32 v[20:21], v[20:21], v[172:173]
	v_add_f32_dpp v28, v46, v34 row_half_mirror row_mask:0xf bank_mask:0xf
	v_add_f32_dpp v32, v47, v35 row_half_mirror row_mask:0xf bank_mask:0xf
	v_pk_mul_f32 v[22:23], v[22:23], v[174:175]
	v_add_f32_dpp v28, v28, v28 row_ror:8 row_mask:0xf bank_mask:0xf
	v_add_f32_dpp v32, v32, v32 row_ror:8 row_mask:0xf bank_mask:0xf
	v_pk_mul_f32 v[24:25], v[24:25], v[172:173]
	v_add_f32_dpp v28, v28, v28 quad_perm:[1,0,3,2] row_mask:0xf bank_mask:0xf
	v_add_f32_dpp v32, v32, v32 quad_perm:[1,0,3,2] row_mask:0xf bank_mask:0xf
	v_pk_mul_f32 v[26:27], v[26:27], v[174:175]
	v_add_f32_dpp v28, v28, v28 quad_perm:[2,3,0,1] row_mask:0xf bank_mask:0xf
	v_add_f32_dpp v32, v32, v32 quad_perm:[2,3,0,1] row_mask:0xf bank_mask:0xf
	v_pk_fma_f32 v[20:21], v[184:185], v[12:13], v[20:21] op_sel_hi:[1,0,1]
	v_mov_b32_dpp v30, v28 row_half_mirror row_mask:0xf bank_mask:0xf
	v_pk_fma_f32 v[22:23], v[186:187], v[12:13], v[22:23] op_sel_hi:[1,0,1]
	v_pk_fma_f32 v[24:25], v[184:185], v[14:15], v[24:25] op_sel_hi:[1,0,1]
	v_pk_fma_f32 v[26:27], v[186:187], v[14:15], v[26:27] op_sel_hi:[1,0,1]
	v_pk_fma_f32 v[20:21], v[92:93], v[28:29], v[20:21] op_sel_hi:[1,0,1] neg_lo:[0,1,0] neg_hi:[0,1,0]
	v_pk_fma_f32 v[22:23], v[94:95], v[28:29], v[22:23] op_sel_hi:[1,0,1] neg_lo:[0,1,0] neg_hi:[0,1,0]
	v_pk_fma_f32 v[24:25], v[92:93], v[30:31], v[24:25] op_sel_hi:[1,0,1] neg_lo:[0,1,0] neg_hi:[0,1,0]
	v_pk_fma_f32 v[26:27], v[94:95], v[30:31], v[26:27] op_sel_hi:[1,0,1] neg_lo:[0,1,0] neg_hi:[0,1,0]
	v_add_f32_e32 v39, v32, v13
	ds_write_b32 v102, v39 offset:3328
	ds_read_b128 v[148:151], v195 offset:7424
	ds_read_b128 v[160:163], v195 offset:15616
	ds_read_b128 v[172:175], v195 offset:32000
	ds_read_b128 v[184:187], v195 offset:23808
	ds_read_b128 v[92:95], v195 offset:40192
	ds_read_b64 v[12:13], v196 offset:14848
	ds_read_b64 v[14:15], v36 offset:14848
	s_waitcnt lgkmcnt(15)
	v_pk_mul_f32 v[46:47], v[24:25], v[140:141] op_sel_hi:[0,1]
	v_pk_mul_f32 v[34:35], v[20:21], v[140:141] op_sel_hi:[0,1]
	v_pk_fma_f32 v[46:47], v[24:25], v[142:143], v[46:47] op_sel:[1,0,0] op_sel_hi:[1,1,1]
	v_pk_fma_f32 v[34:35], v[20:21], v[142:143], v[34:35] op_sel:[1,0,0] op_sel_hi:[1,1,1]
	v_pk_fma_f32 v[46:47], v[26:27], v[152:153], v[46:47] op_sel_hi:[0,1,1]
	v_pk_fma_f32 v[34:35], v[22:23], v[152:153], v[34:35] op_sel_hi:[0,1,1]
	v_pk_fma_f32 v[46:47], v[26:27], v[154:155], v[46:47] op_sel:[1,0,0] op_sel_hi:[1,1,1]
	v_pk_fma_f32 v[34:35], v[22:23], v[154:155], v[34:35] op_sel:[1,0,0] op_sel_hi:[1,1,1]
	v_pk_mul_f32 v[20:21], v[20:21], v[164:165]
	v_add_f32_dpp v28, v46, v34 row_half_mirror row_mask:0xf bank_mask:0xf
	v_add_f32_dpp v32, v47, v35 row_half_mirror row_mask:0xf bank_mask:0xf
	v_pk_mul_f32 v[22:23], v[22:23], v[166:167]
	v_add_f32_dpp v28, v28, v28 row_ror:8 row_mask:0xf bank_mask:0xf
	v_add_f32_dpp v32, v32, v32 row_ror:8 row_mask:0xf bank_mask:0xf
	v_pk_mul_f32 v[24:25], v[24:25], v[164:165]
	v_add_f32_dpp v28, v28, v28 quad_perm:[1,0,3,2] row_mask:0xf bank_mask:0xf
	v_add_f32_dpp v32, v32, v32 quad_perm:[1,0,3,2] row_mask:0xf bank_mask:0xf
	v_pk_mul_f32 v[26:27], v[26:27], v[166:167]
	v_add_f32_dpp v28, v28, v28 quad_perm:[2,3,0,1] row_mask:0xf bank_mask:0xf
	v_add_f32_dpp v32, v32, v32 quad_perm:[2,3,0,1] row_mask:0xf bank_mask:0xf
	v_pk_fma_f32 v[20:21], v[176:177], v[4:5], v[20:21] op_sel_hi:[1,0,1]
	v_mov_b32_dpp v30, v28 row_half_mirror row_mask:0xf bank_mask:0xf
	v_pk_fma_f32 v[22:23], v[178:179], v[4:5], v[22:23] op_sel_hi:[1,0,1]
	v_pk_fma_f32 v[24:25], v[176:177], v[6:7], v[24:25] op_sel_hi:[1,0,1]
	v_pk_fma_f32 v[26:27], v[178:179], v[6:7], v[26:27] op_sel_hi:[1,0,1]
	v_pk_fma_f32 v[20:21], v[84:85], v[28:29], v[20:21] op_sel_hi:[1,0,1] neg_lo:[0,1,0] neg_hi:[0,1,0]
	v_pk_fma_f32 v[22:23], v[86:87], v[28:29], v[22:23] op_sel_hi:[1,0,1] neg_lo:[0,1,0] neg_hi:[0,1,0]
	v_pk_fma_f32 v[24:25], v[84:85], v[30:31], v[24:25] op_sel_hi:[1,0,1] neg_lo:[0,1,0] neg_hi:[0,1,0]
	v_pk_fma_f32 v[26:27], v[86:87], v[30:31], v[26:27] op_sel_hi:[1,0,1] neg_lo:[0,1,0] neg_hi:[0,1,0]
	v_add_f32_e32 v39, v32, v5
	ds_write_b32 v102, v39 offset:3456
	ds_read_b128 v[140:143], v195 offset:7680
	ds_read_b128 v[152:155], v195 offset:15872
	ds_read_b128 v[164:167], v195 offset:32256
	ds_read_b128 v[176:179], v195 offset:24064
	ds_read_b128 v[84:87], v195 offset:40448
	ds_read_b64 v[4:5], v196 offset:15360
	ds_read_b64 v[6:7], v36 offset:15360
	s_waitcnt lgkmcnt(15)
	v_pk_mul_f32 v[46:47], v[24:25], v[144:145] op_sel_hi:[0,1]
	v_pk_mul_f32 v[34:35], v[20:21], v[144:145] op_sel_hi:[0,1]
	v_pk_fma_f32 v[46:47], v[24:25], v[146:147], v[46:47] op_sel:[1,0,0] op_sel_hi:[1,1,1]
	v_pk_fma_f32 v[34:35], v[20:21], v[146:147], v[34:35] op_sel:[1,0,0] op_sel_hi:[1,1,1]
	v_pk_fma_f32 v[46:47], v[26:27], v[156:157], v[46:47] op_sel_hi:[0,1,1]
	v_pk_fma_f32 v[34:35], v[22:23], v[156:157], v[34:35] op_sel_hi:[0,1,1]
	v_pk_fma_f32 v[46:47], v[26:27], v[158:159], v[46:47] op_sel:[1,0,0] op_sel_hi:[1,1,1]
	v_pk_fma_f32 v[34:35], v[22:23], v[158:159], v[34:35] op_sel:[1,0,0] op_sel_hi:[1,1,1]
	v_pk_mul_f32 v[20:21], v[20:21], v[168:169]
	v_add_f32_dpp v28, v46, v34 row_half_mirror row_mask:0xf bank_mask:0xf
	v_add_f32_dpp v32, v47, v35 row_half_mirror row_mask:0xf bank_mask:0xf
	v_pk_mul_f32 v[22:23], v[22:23], v[170:171]
	v_add_f32_dpp v28, v28, v28 row_ror:8 row_mask:0xf bank_mask:0xf
	v_add_f32_dpp v32, v32, v32 row_ror:8 row_mask:0xf bank_mask:0xf
	v_pk_mul_f32 v[24:25], v[24:25], v[168:169]
	v_add_f32_dpp v28, v28, v28 quad_perm:[1,0,3,2] row_mask:0xf bank_mask:0xf
	v_add_f32_dpp v32, v32, v32 quad_perm:[1,0,3,2] row_mask:0xf bank_mask:0xf
	v_pk_mul_f32 v[26:27], v[26:27], v[170:171]
	v_add_f32_dpp v28, v28, v28 quad_perm:[2,3,0,1] row_mask:0xf bank_mask:0xf
	v_add_f32_dpp v32, v32, v32 quad_perm:[2,3,0,1] row_mask:0xf bank_mask:0xf
	v_pk_fma_f32 v[20:21], v[180:181], v[8:9], v[20:21] op_sel_hi:[1,0,1]
	v_mov_b32_dpp v30, v28 row_half_mirror row_mask:0xf bank_mask:0xf
	v_pk_fma_f32 v[22:23], v[182:183], v[8:9], v[22:23] op_sel_hi:[1,0,1]
	v_pk_fma_f32 v[24:25], v[180:181], v[10:11], v[24:25] op_sel_hi:[1,0,1]
	v_pk_fma_f32 v[26:27], v[182:183], v[10:11], v[26:27] op_sel_hi:[1,0,1]
	v_pk_fma_f32 v[20:21], v[88:89], v[28:29], v[20:21] op_sel_hi:[1,0,1] neg_lo:[0,1,0] neg_hi:[0,1,0]
	v_pk_fma_f32 v[22:23], v[90:91], v[28:29], v[22:23] op_sel_hi:[1,0,1] neg_lo:[0,1,0] neg_hi:[0,1,0]
	v_pk_fma_f32 v[24:25], v[88:89], v[30:31], v[24:25] op_sel_hi:[1,0,1] neg_lo:[0,1,0] neg_hi:[0,1,0]
	v_pk_fma_f32 v[26:27], v[90:91], v[30:31], v[26:27] op_sel_hi:[1,0,1] neg_lo:[0,1,0] neg_hi:[0,1,0]
	v_add_f32_e32 v39, v32, v9
	ds_write_b32 v102, v39 offset:3584
	ds_read_b128 v[144:147], v195 offset:7936
	ds_read_b128 v[156:159], v195 offset:16128
	ds_read_b128 v[168:171], v195 offset:32512
	ds_read_b128 v[180:183], v195 offset:24320
	ds_read_b128 v[88:91], v195 offset:40704
	ds_read_b64 v[8:9], v196 offset:15872
	ds_read_b64 v[10:11], v36 offset:15872
	s_waitcnt lgkmcnt(15)
	v_pk_mul_f32 v[46:47], v[24:25], v[148:149] op_sel_hi:[0,1]
	v_pk_mul_f32 v[34:35], v[20:21], v[148:149] op_sel_hi:[0,1]
	v_pk_fma_f32 v[46:47], v[24:25], v[150:151], v[46:47] op_sel:[1,0,0] op_sel_hi:[1,1,1]
	v_pk_fma_f32 v[34:35], v[20:21], v[150:151], v[34:35] op_sel:[1,0,0] op_sel_hi:[1,1,1]
	v_pk_fma_f32 v[46:47], v[26:27], v[160:161], v[46:47] op_sel_hi:[0,1,1]
	v_pk_fma_f32 v[34:35], v[22:23], v[160:161], v[34:35] op_sel_hi:[0,1,1]
	v_pk_fma_f32 v[46:47], v[26:27], v[162:163], v[46:47] op_sel:[1,0,0] op_sel_hi:[1,1,1]
	v_pk_fma_f32 v[34:35], v[22:23], v[162:163], v[34:35] op_sel:[1,0,0] op_sel_hi:[1,1,1]
	v_pk_mul_f32 v[20:21], v[20:21], v[172:173]
	v_add_f32_dpp v28, v46, v34 row_half_mirror row_mask:0xf bank_mask:0xf
	v_add_f32_dpp v32, v47, v35 row_half_mirror row_mask:0xf bank_mask:0xf
	v_pk_mul_f32 v[22:23], v[22:23], v[174:175]
	v_add_f32_dpp v28, v28, v28 row_ror:8 row_mask:0xf bank_mask:0xf
	v_add_f32_dpp v32, v32, v32 row_ror:8 row_mask:0xf bank_mask:0xf
	v_pk_mul_f32 v[24:25], v[24:25], v[172:173]
	v_add_f32_dpp v28, v28, v28 quad_perm:[1,0,3,2] row_mask:0xf bank_mask:0xf
	v_add_f32_dpp v32, v32, v32 quad_perm:[1,0,3,2] row_mask:0xf bank_mask:0xf
	v_pk_mul_f32 v[26:27], v[26:27], v[174:175]
	v_add_f32_dpp v28, v28, v28 quad_perm:[2,3,0,1] row_mask:0xf bank_mask:0xf
	v_add_f32_dpp v32, v32, v32 quad_perm:[2,3,0,1] row_mask:0xf bank_mask:0xf
	v_pk_fma_f32 v[20:21], v[184:185], v[12:13], v[20:21] op_sel_hi:[1,0,1]
	v_mov_b32_dpp v30, v28 row_half_mirror row_mask:0xf bank_mask:0xf
	v_pk_fma_f32 v[22:23], v[186:187], v[12:13], v[22:23] op_sel_hi:[1,0,1]
	v_pk_fma_f32 v[24:25], v[184:185], v[14:15], v[24:25] op_sel_hi:[1,0,1]
	v_pk_fma_f32 v[26:27], v[186:187], v[14:15], v[26:27] op_sel_hi:[1,0,1]
	v_pk_fma_f32 v[20:21], v[92:93], v[28:29], v[20:21] op_sel_hi:[1,0,1] neg_lo:[0,1,0] neg_hi:[0,1,0]
	v_pk_fma_f32 v[22:23], v[94:95], v[28:29], v[22:23] op_sel_hi:[1,0,1] neg_lo:[0,1,0] neg_hi:[0,1,0]
	v_pk_fma_f32 v[24:25], v[92:93], v[30:31], v[24:25] op_sel_hi:[1,0,1] neg_lo:[0,1,0] neg_hi:[0,1,0]
	v_pk_fma_f32 v[26:27], v[94:95], v[30:31], v[26:27] op_sel_hi:[1,0,1] neg_lo:[0,1,0] neg_hi:[0,1,0]
	v_add_f32_e32 v39, v32, v13
	ds_write_b32 v102, v39 offset:3712
	s_waitcnt lgkmcnt(9)
	v_pk_mul_f32 v[46:47], v[24:25], v[140:141] op_sel_hi:[0,1]
	v_pk_mul_f32 v[34:35], v[20:21], v[140:141] op_sel_hi:[0,1]
	v_pk_fma_f32 v[46:47], v[24:25], v[142:143], v[46:47] op_sel:[1,0,0] op_sel_hi:[1,1,1]
	v_pk_fma_f32 v[34:35], v[20:21], v[142:143], v[34:35] op_sel:[1,0,0] op_sel_hi:[1,1,1]
	v_pk_fma_f32 v[46:47], v[26:27], v[152:153], v[46:47] op_sel_hi:[0,1,1]
	v_pk_fma_f32 v[34:35], v[22:23], v[152:153], v[34:35] op_sel_hi:[0,1,1]
	v_pk_fma_f32 v[46:47], v[26:27], v[154:155], v[46:47] op_sel:[1,0,0] op_sel_hi:[1,1,1]
	v_pk_fma_f32 v[34:35], v[22:23], v[154:155], v[34:35] op_sel:[1,0,0] op_sel_hi:[1,1,1]
	v_pk_mul_f32 v[20:21], v[20:21], v[164:165]
	v_add_f32_dpp v28, v46, v34 row_half_mirror row_mask:0xf bank_mask:0xf
	v_add_f32_dpp v32, v47, v35 row_half_mirror row_mask:0xf bank_mask:0xf
	v_pk_mul_f32 v[22:23], v[22:23], v[166:167]
	v_add_f32_dpp v28, v28, v28 row_ror:8 row_mask:0xf bank_mask:0xf
	v_add_f32_dpp v32, v32, v32 row_ror:8 row_mask:0xf bank_mask:0xf
	v_pk_mul_f32 v[24:25], v[24:25], v[164:165]
	v_add_f32_dpp v28, v28, v28 quad_perm:[1,0,3,2] row_mask:0xf bank_mask:0xf
	v_add_f32_dpp v32, v32, v32 quad_perm:[1,0,3,2] row_mask:0xf bank_mask:0xf
	v_pk_mul_f32 v[26:27], v[26:27], v[166:167]
	v_add_f32_dpp v28, v28, v28 quad_perm:[2,3,0,1] row_mask:0xf bank_mask:0xf
	v_add_f32_dpp v32, v32, v32 quad_perm:[2,3,0,1] row_mask:0xf bank_mask:0xf
	v_pk_fma_f32 v[20:21], v[176:177], v[4:5], v[20:21] op_sel_hi:[1,0,1]
	v_mov_b32_dpp v30, v28 row_half_mirror row_mask:0xf bank_mask:0xf
	v_pk_fma_f32 v[22:23], v[178:179], v[4:5], v[22:23] op_sel_hi:[1,0,1]
	v_pk_fma_f32 v[24:25], v[176:177], v[6:7], v[24:25] op_sel_hi:[1,0,1]
	v_pk_fma_f32 v[26:27], v[178:179], v[6:7], v[26:27] op_sel_hi:[1,0,1]
	v_pk_fma_f32 v[20:21], v[84:85], v[28:29], v[20:21] op_sel_hi:[1,0,1] neg_lo:[0,1,0] neg_hi:[0,1,0]
	v_pk_fma_f32 v[22:23], v[86:87], v[28:29], v[22:23] op_sel_hi:[1,0,1] neg_lo:[0,1,0] neg_hi:[0,1,0]
	v_pk_fma_f32 v[24:25], v[84:85], v[30:31], v[24:25] op_sel_hi:[1,0,1] neg_lo:[0,1,0] neg_hi:[0,1,0]
	v_pk_fma_f32 v[26:27], v[86:87], v[30:31], v[26:27] op_sel_hi:[1,0,1] neg_lo:[0,1,0] neg_hi:[0,1,0]
	v_add_f32_e32 v39, v32, v5
	ds_write_b32 v102, v39 offset:3840
	s_waitcnt lgkmcnt(2)
	v_pk_mul_f32 v[46:47], v[24:25], v[144:145] op_sel_hi:[0,1]
	v_pk_mul_f32 v[34:35], v[20:21], v[144:145] op_sel_hi:[0,1]
	v_pk_fma_f32 v[46:47], v[24:25], v[146:147], v[46:47] op_sel:[1,0,0] op_sel_hi:[1,1,1]
	v_pk_fma_f32 v[34:35], v[20:21], v[146:147], v[34:35] op_sel:[1,0,0] op_sel_hi:[1,1,1]
	v_pk_fma_f32 v[46:47], v[26:27], v[156:157], v[46:47] op_sel_hi:[0,1,1]
	v_pk_fma_f32 v[34:35], v[22:23], v[156:157], v[34:35] op_sel_hi:[0,1,1]
	v_pk_fma_f32 v[46:47], v[26:27], v[158:159], v[46:47] op_sel:[1,0,0] op_sel_hi:[1,1,1]
	v_pk_fma_f32 v[34:35], v[22:23], v[158:159], v[34:35] op_sel:[1,0,0] op_sel_hi:[1,1,1]
	v_pk_mul_f32 v[20:21], v[20:21], v[168:169]
	v_add_f32_dpp v28, v46, v34 row_half_mirror row_mask:0xf bank_mask:0xf
	v_add_f32_dpp v32, v47, v35 row_half_mirror row_mask:0xf bank_mask:0xf
	v_pk_mul_f32 v[22:23], v[22:23], v[170:171]
	v_add_f32_dpp v28, v28, v28 row_ror:8 row_mask:0xf bank_mask:0xf
	v_add_f32_dpp v32, v32, v32 row_ror:8 row_mask:0xf bank_mask:0xf
	v_pk_mul_f32 v[24:25], v[24:25], v[168:169]
	v_add_f32_dpp v28, v28, v28 quad_perm:[1,0,3,2] row_mask:0xf bank_mask:0xf
	v_add_f32_dpp v32, v32, v32 quad_perm:[1,0,3,2] row_mask:0xf bank_mask:0xf
	v_pk_mul_f32 v[26:27], v[26:27], v[170:171]
	v_add_f32_dpp v28, v28, v28 quad_perm:[2,3,0,1] row_mask:0xf bank_mask:0xf
	v_add_f32_dpp v32, v32, v32 quad_perm:[2,3,0,1] row_mask:0xf bank_mask:0xf
	v_pk_fma_f32 v[20:21], v[180:181], v[8:9], v[20:21] op_sel_hi:[1,0,1]
	v_mov_b32_dpp v30, v28 row_half_mirror row_mask:0xf bank_mask:0xf
	v_pk_fma_f32 v[22:23], v[182:183], v[8:9], v[22:23] op_sel_hi:[1,0,1]
	v_pk_fma_f32 v[24:25], v[180:181], v[10:11], v[24:25] op_sel_hi:[1,0,1]
	v_pk_fma_f32 v[26:27], v[182:183], v[10:11], v[26:27] op_sel_hi:[1,0,1]
	v_pk_fma_f32 v[20:21], v[88:89], v[28:29], v[20:21] op_sel_hi:[1,0,1] neg_lo:[0,1,0] neg_hi:[0,1,0]
	v_pk_fma_f32 v[22:23], v[90:91], v[28:29], v[22:23] op_sel_hi:[1,0,1] neg_lo:[0,1,0] neg_hi:[0,1,0]
	v_pk_fma_f32 v[24:25], v[88:89], v[30:31], v[24:25] op_sel_hi:[1,0,1] neg_lo:[0,1,0] neg_hi:[0,1,0]
	v_pk_fma_f32 v[26:27], v[90:91], v[30:31], v[26:27] op_sel_hi:[1,0,1] neg_lo:[0,1,0] neg_hi:[0,1,0]
	v_add_f32_e32 v39, v32, v9
	ds_write_b32 v102, v39 offset:3968
	s_waitcnt lgkmcnt(0)
	s_barrier
	s_add_i32 s8, s8, 1
	s_cmp_eq_u32 s8, 64
	s_cbranch_scc0 .Lrw_scan_loop
	s_setprio 0
	s_branch .LBB0_183
